# phase-0 modulation GEMV rewritten: 64 weight loads in flight (was one dependent round trip per weight), silu once per k + v_readlane broadcast
# speedup vs baseline: 1.0585x; 1.0361x over previous
.LBB0_106:
	s_andn2_b64 vcc, exec, s[4:5]
	s_cbranch_vccnz .LBB0_29
	s_mul_hi_i32 s4, s71, 0x2aaaaaab
	s_lshr_b32 s5, s4, 31
	s_ashr_i32 s22, s4, 4
	s_add_i32 s22, s22, s5
	v_ashrrev_i32_e32 v0, 6, v50
	s_mul_i32 s4, s22, 0x60
	s_waitcnt lgkmcnt(0)
	v_lshlrev_b32_e32 v2, 8, v0
	s_sub_i32 s4, s71, s4
	v_and_b32_e32 v51, 63, v50
	v_ashrrev_i32_e32 v3, 31, v2
	v_readlane_b32 s52, v254, 42
	v_lshl_or_b32 v52, s4, 6, v51
	v_lshlrev_b64 v[4:5], 2, v[2:3]
	v_readlane_b32 s53, v254, 43
	v_mad_i64_i32 v[2:3], s[4:5], v2, s37, 0
	v_mov_b32_e32 v6, 0x1800000
	v_ashrrev_i32_e32 v53, 31, v52
	v_readlane_b32 s54, v254, 44
	v_readlane_b32 s55, v254, 45
	v_readlane_b32 s56, v254, 46
	v_readlane_b32 s57, v254, 47
	v_readlane_b32 s58, v254, 48
	v_readlane_b32 s59, v254, 49
	v_readlane_b32 s60, v254, 50
	v_readlane_b32 s61, v254, 51
	s_mov_b64 s[40:41], s[52:53]
	v_mad_i64_i32 v[2:3], s[4:5], s22, v6, v[2:3]
	s_mov_b64 s[46:47], s[58:59]
	s_mov_b64 s[48:49], s[60:61]
	v_lshl_add_u64 v[2:3], v[52:53], 2, v[2:3]
	v_mov_b32_e32 v66, 0
	v_lshl_add_u64 v[54:55], s[46:47], 0, v[4:5]
	v_lshl_add_u64 v[56:57], s[34:35], 0, v[2:3]
	v_lshl_add_u64 v[58:59], s[48:49], 0, v[4:5]
	s_mov_b64 s[4:5], 0
	v_mov_b32_e32 v10, 0
	v_mov_b32_e32 v11, v66
	v_readlane_b32 s62, v254, 52
	v_readlane_b32 s63, v254, 53
	v_readlane_b32 s64, v254, 54
	v_readlane_b32 s65, v254, 55
	v_readlane_b32 s66, v254, 56
	v_readlane_b32 s67, v254, 57
	s_mov_b64 s[42:43], s[54:55]
	s_mov_b64 s[44:45], s[56:57]
	v_lshlrev_b32_e32 v2, 4, v51
	v_mov_b32_e32 v3, v1
	v_lshl_add_u64 v[4:5], v[58:59], 0, v[2:3]
	v_lshl_add_u64 v[6:7], v[54:55], 0, v[2:3]
	v_lshl_add_u64 v[2:3], v[6:7], 0, s[8:9]
	global_load_dwordx4 v[12:15], v[4:5], off
	global_load_dwordx4 v[16:19], v[6:7], off
	global_load_dwordx4 v[20:23], v[2:3], off
	v_mov_b32_e32 v8, 0x6000
	v_mov_b32_e32 v9, v1
	v_add_co_u32_e32 v56, vcc, 0xfff46000, v56
	s_nop 1
	v_addc_co_u32_e32 v57, vcc, -1, v57, vcc
	global_load_dword v70, v[56:57], off
	v_lshl_add_u64 v[56:57], v[56:57], 0, v[8:9]
	global_load_dword v71, v[56:57], off
	v_lshl_add_u64 v[56:57], v[56:57], 0, v[8:9]
	global_load_dword v72, v[56:57], off
	v_lshl_add_u64 v[56:57], v[56:57], 0, v[8:9]
	global_load_dword v73, v[56:57], off
	v_lshl_add_u64 v[56:57], v[56:57], 0, v[8:9]
	global_load_dword v74, v[56:57], off
	v_lshl_add_u64 v[56:57], v[56:57], 0, v[8:9]
	global_load_dword v75, v[56:57], off
	v_lshl_add_u64 v[56:57], v[56:57], 0, v[8:9]
	global_load_dword v76, v[56:57], off
	v_lshl_add_u64 v[56:57], v[56:57], 0, v[8:9]
	global_load_dword v77, v[56:57], off
	v_lshl_add_u64 v[56:57], v[56:57], 0, v[8:9]
	global_load_dword v78, v[56:57], off
	v_lshl_add_u64 v[56:57], v[56:57], 0, v[8:9]
	global_load_dword v79, v[56:57], off
	v_lshl_add_u64 v[56:57], v[56:57], 0, v[8:9]
	global_load_dword v80, v[56:57], off
	v_lshl_add_u64 v[56:57], v[56:57], 0, v[8:9]
	global_load_dword v81, v[56:57], off
	v_lshl_add_u64 v[56:57], v[56:57], 0, v[8:9]
	global_load_dword v82, v[56:57], off
	v_lshl_add_u64 v[56:57], v[56:57], 0, v[8:9]
	global_load_dword v83, v[56:57], off
	v_lshl_add_u64 v[56:57], v[56:57], 0, v[8:9]
	global_load_dword v84, v[56:57], off
	v_lshl_add_u64 v[56:57], v[56:57], 0, v[8:9]
	global_load_dword v85, v[56:57], off
	v_lshl_add_u64 v[56:57], v[56:57], 0, v[8:9]
	global_load_dword v86, v[56:57], off
	v_lshl_add_u64 v[56:57], v[56:57], 0, v[8:9]
	global_load_dword v87, v[56:57], off
	v_lshl_add_u64 v[56:57], v[56:57], 0, v[8:9]
	global_load_dword v88, v[56:57], off
	v_lshl_add_u64 v[56:57], v[56:57], 0, v[8:9]
	global_load_dword v89, v[56:57], off
	v_lshl_add_u64 v[56:57], v[56:57], 0, v[8:9]
	global_load_dword v90, v[56:57], off
	v_lshl_add_u64 v[56:57], v[56:57], 0, v[8:9]
	global_load_dword v91, v[56:57], off
	v_lshl_add_u64 v[56:57], v[56:57], 0, v[8:9]
	global_load_dword v92, v[56:57], off
	v_lshl_add_u64 v[56:57], v[56:57], 0, v[8:9]
	global_load_dword v93, v[56:57], off
	v_lshl_add_u64 v[56:57], v[56:57], 0, v[8:9]
	global_load_dword v94, v[56:57], off
	v_lshl_add_u64 v[56:57], v[56:57], 0, v[8:9]
	global_load_dword v95, v[56:57], off
	v_lshl_add_u64 v[56:57], v[56:57], 0, v[8:9]
	global_load_dword v96, v[56:57], off
	v_lshl_add_u64 v[56:57], v[56:57], 0, v[8:9]
	global_load_dword v97, v[56:57], off
	v_lshl_add_u64 v[56:57], v[56:57], 0, v[8:9]
	global_load_dword v98, v[56:57], off
	v_lshl_add_u64 v[56:57], v[56:57], 0, v[8:9]
	global_load_dword v99, v[56:57], off
	v_lshl_add_u64 v[56:57], v[56:57], 0, v[8:9]
	global_load_dword v100, v[56:57], off
	v_lshl_add_u64 v[56:57], v[56:57], 0, v[8:9]
	global_load_dword v101, v[56:57], off
	v_lshl_add_u64 v[56:57], v[56:57], 0, v[8:9]
	global_load_dword v102, v[56:57], off
	v_lshl_add_u64 v[56:57], v[56:57], 0, v[8:9]
	global_load_dword v103, v[56:57], off
	v_lshl_add_u64 v[56:57], v[56:57], 0, v[8:9]
	global_load_dword v104, v[56:57], off
	v_lshl_add_u64 v[56:57], v[56:57], 0, v[8:9]
	global_load_dword v105, v[56:57], off
	v_lshl_add_u64 v[56:57], v[56:57], 0, v[8:9]
	global_load_dword v106, v[56:57], off
	v_lshl_add_u64 v[56:57], v[56:57], 0, v[8:9]
	global_load_dword v107, v[56:57], off
	v_lshl_add_u64 v[56:57], v[56:57], 0, v[8:9]
	global_load_dword v108, v[56:57], off
	v_lshl_add_u64 v[56:57], v[56:57], 0, v[8:9]
	global_load_dword v109, v[56:57], off
	v_lshl_add_u64 v[56:57], v[56:57], 0, v[8:9]
	global_load_dword v110, v[56:57], off
	v_lshl_add_u64 v[56:57], v[56:57], 0, v[8:9]
	global_load_dword v111, v[56:57], off
	v_lshl_add_u64 v[56:57], v[56:57], 0, v[8:9]
	global_load_dword v112, v[56:57], off
	v_lshl_add_u64 v[56:57], v[56:57], 0, v[8:9]
	global_load_dword v113, v[56:57], off
	v_lshl_add_u64 v[56:57], v[56:57], 0, v[8:9]
	global_load_dword v114, v[56:57], off
	v_lshl_add_u64 v[56:57], v[56:57], 0, v[8:9]
	global_load_dword v115, v[56:57], off
	v_lshl_add_u64 v[56:57], v[56:57], 0, v[8:9]
	global_load_dword v116, v[56:57], off
	v_lshl_add_u64 v[56:57], v[56:57], 0, v[8:9]
	global_load_dword v117, v[56:57], off
	v_lshl_add_u64 v[56:57], v[56:57], 0, v[8:9]
	s_waitcnt vmcnt(48)
	v_mul_f32_e32 v24, 0xbfb8aa3b, v12
	v_mul_f32_e32 v25, 0xbfb8aa3b, v13
	v_mul_f32_e32 v26, 0xbfb8aa3b, v14
	v_mul_f32_e32 v27, 0xbfb8aa3b, v15
	v_exp_f32_e32 v24, v24
	v_exp_f32_e32 v25, v25
	v_exp_f32_e32 v26, v26
	v_exp_f32_e32 v27, v27
	v_add_f32_e32 v24, 1.0, v24
	v_add_f32_e32 v25, 1.0, v25
	v_add_f32_e32 v26, 1.0, v26
	v_add_f32_e32 v27, 1.0, v27
	v_rcp_f32_e32 v24, v24
	v_rcp_f32_e32 v25, v25
	v_rcp_f32_e32 v26, v26
	v_rcp_f32_e32 v27, v27
	s_nop 0
	v_mul_f32_e32 v12, v12, v24
	v_mul_f32_e32 v13, v13, v25
	v_mul_f32_e32 v14, v14, v26
	v_mul_f32_e32 v15, v15, v27
	v_mul_f32_e32 v28, 0xbfb8aa3b, v16
	v_mul_f32_e32 v29, 0xbfb8aa3b, v17
	v_mul_f32_e32 v30, 0xbfb8aa3b, v18
	v_mul_f32_e32 v31, 0xbfb8aa3b, v19
	v_exp_f32_e32 v28, v28
	v_exp_f32_e32 v29, v29
	v_exp_f32_e32 v30, v30
	v_exp_f32_e32 v31, v31
	v_add_f32_e32 v28, 1.0, v28
	v_add_f32_e32 v29, 1.0, v29
	v_add_f32_e32 v30, 1.0, v30
	v_add_f32_e32 v31, 1.0, v31
	v_rcp_f32_e32 v28, v28
	v_rcp_f32_e32 v29, v29
	v_rcp_f32_e32 v30, v30
	v_rcp_f32_e32 v31, v31
	s_nop 0
	v_mul_f32_e32 v16, v16, v28
	v_mul_f32_e32 v17, v17, v29
	v_mul_f32_e32 v18, v18, v30
	v_mul_f32_e32 v19, v19, v31
	v_mul_f32_e32 v32, 0xbfb8aa3b, v20
	v_mul_f32_e32 v33, 0xbfb8aa3b, v21
	v_mul_f32_e32 v34, 0xbfb8aa3b, v22
	v_mul_f32_e32 v35, 0xbfb8aa3b, v23
	v_exp_f32_e32 v32, v32
	v_exp_f32_e32 v33, v33
	v_exp_f32_e32 v34, v34
	v_exp_f32_e32 v35, v35
	v_add_f32_e32 v32, 1.0, v32
	v_add_f32_e32 v33, 1.0, v33
	v_add_f32_e32 v34, 1.0, v34
	v_add_f32_e32 v35, 1.0, v35
	v_rcp_f32_e32 v32, v32
	v_rcp_f32_e32 v33, v33
	v_rcp_f32_e32 v34, v34
	v_rcp_f32_e32 v35, v35
	s_nop 0
	v_mul_f32_e32 v20, v20, v32
	v_mul_f32_e32 v21, v21, v33
	v_mul_f32_e32 v22, v22, v34
	v_mul_f32_e32 v23, v23, v35
	global_load_dword v118, v[56:57], off
	v_lshl_add_u64 v[56:57], v[56:57], 0, v[8:9]
	global_load_dword v119, v[56:57], off
	v_lshl_add_u64 v[56:57], v[56:57], 0, v[8:9]
	global_load_dword v120, v[56:57], off
	v_lshl_add_u64 v[56:57], v[56:57], 0, v[8:9]
	global_load_dword v121, v[56:57], off
	v_lshl_add_u64 v[56:57], v[56:57], 0, v[8:9]
	global_load_dword v122, v[56:57], off
	v_lshl_add_u64 v[56:57], v[56:57], 0, v[8:9]
	global_load_dword v123, v[56:57], off
	v_lshl_add_u64 v[56:57], v[56:57], 0, v[8:9]
	global_load_dword v124, v[56:57], off
	v_lshl_add_u64 v[56:57], v[56:57], 0, v[8:9]
	global_load_dword v125, v[56:57], off
	v_lshl_add_u64 v[56:57], v[56:57], 0, v[8:9]
	global_load_dword v126, v[56:57], off
	v_lshl_add_u64 v[56:57], v[56:57], 0, v[8:9]
	global_load_dword v127, v[56:57], off
	v_lshl_add_u64 v[56:57], v[56:57], 0, v[8:9]
	global_load_dword v128, v[56:57], off
	v_lshl_add_u64 v[56:57], v[56:57], 0, v[8:9]
	global_load_dword v129, v[56:57], off
	v_lshl_add_u64 v[56:57], v[56:57], 0, v[8:9]
	global_load_dword v130, v[56:57], off
	v_lshl_add_u64 v[56:57], v[56:57], 0, v[8:9]
	global_load_dword v131, v[56:57], off
	v_lshl_add_u64 v[56:57], v[56:57], 0, v[8:9]
	global_load_dword v132, v[56:57], off
	v_lshl_add_u64 v[56:57], v[56:57], 0, v[8:9]
	global_load_dword v133, v[56:57], off
	v_lshl_add_u64 v[56:57], v[56:57], 0, v[8:9]
	s_waitcnt vmcnt(48)
	v_readlane_b32 s20, v12, 0
	v_readlane_b32 s21, v16, 0
	v_readlane_b32 vcc_lo, v20, 0
	v_fmac_f32_e32 v10, s20, v70
	v_fmac_f32_e32 v11, s21, v70
	v_fmac_f32_e32 v66, vcc_lo, v70
	v_readlane_b32 s20, v13, 0
	v_readlane_b32 s21, v17, 0
	v_readlane_b32 vcc_lo, v21, 0
	v_fmac_f32_e32 v10, s20, v71
	v_fmac_f32_e32 v11, s21, v71
	v_fmac_f32_e32 v66, vcc_lo, v71
	v_readlane_b32 s20, v14, 0
	v_readlane_b32 s21, v18, 0
	v_readlane_b32 vcc_lo, v22, 0
	v_fmac_f32_e32 v10, s20, v72
	v_fmac_f32_e32 v11, s21, v72
	v_fmac_f32_e32 v66, vcc_lo, v72
	v_readlane_b32 s20, v15, 0
	v_readlane_b32 s21, v19, 0
	v_readlane_b32 vcc_lo, v23, 0
	v_fmac_f32_e32 v10, s20, v73
	v_fmac_f32_e32 v11, s21, v73
	v_fmac_f32_e32 v66, vcc_lo, v73
	v_readlane_b32 s20, v12, 1
	v_readlane_b32 s21, v16, 1
	v_readlane_b32 vcc_lo, v20, 1
	v_fmac_f32_e32 v10, s20, v74
	v_fmac_f32_e32 v11, s21, v74
	v_fmac_f32_e32 v66, vcc_lo, v74
	v_readlane_b32 s20, v13, 1
	v_readlane_b32 s21, v17, 1
	v_readlane_b32 vcc_lo, v21, 1
	v_fmac_f32_e32 v10, s20, v75
	v_fmac_f32_e32 v11, s21, v75
	v_fmac_f32_e32 v66, vcc_lo, v75
	v_readlane_b32 s20, v14, 1
	v_readlane_b32 s21, v18, 1
	v_readlane_b32 vcc_lo, v22, 1
	v_fmac_f32_e32 v10, s20, v76
	v_fmac_f32_e32 v11, s21, v76
	v_fmac_f32_e32 v66, vcc_lo, v76
	v_readlane_b32 s20, v15, 1
	v_readlane_b32 s21, v19, 1
	v_readlane_b32 vcc_lo, v23, 1
	v_fmac_f32_e32 v10, s20, v77
	v_fmac_f32_e32 v11, s21, v77
	v_fmac_f32_e32 v66, vcc_lo, v77
	v_readlane_b32 s20, v12, 2
	v_readlane_b32 s21, v16, 2
	v_readlane_b32 vcc_lo, v20, 2
	v_fmac_f32_e32 v10, s20, v78
	v_fmac_f32_e32 v11, s21, v78
	v_fmac_f32_e32 v66, vcc_lo, v78
	v_readlane_b32 s20, v13, 2
	v_readlane_b32 s21, v17, 2
	v_readlane_b32 vcc_lo, v21, 2
	v_fmac_f32_e32 v10, s20, v79
	v_fmac_f32_e32 v11, s21, v79
	v_fmac_f32_e32 v66, vcc_lo, v79
	v_readlane_b32 s20, v14, 2
	v_readlane_b32 s21, v18, 2
	v_readlane_b32 vcc_lo, v22, 2
	v_fmac_f32_e32 v10, s20, v80
	v_fmac_f32_e32 v11, s21, v80
	v_fmac_f32_e32 v66, vcc_lo, v80
	v_readlane_b32 s20, v15, 2
	v_readlane_b32 s21, v19, 2
	v_readlane_b32 vcc_lo, v23, 2
	v_fmac_f32_e32 v10, s20, v81
	v_fmac_f32_e32 v11, s21, v81
	v_fmac_f32_e32 v66, vcc_lo, v81
	v_readlane_b32 s20, v12, 3
	v_readlane_b32 s21, v16, 3
	v_readlane_b32 vcc_lo, v20, 3
	v_fmac_f32_e32 v10, s20, v82
	v_fmac_f32_e32 v11, s21, v82
	v_fmac_f32_e32 v66, vcc_lo, v82
	v_readlane_b32 s20, v13, 3
	v_readlane_b32 s21, v17, 3
	v_readlane_b32 vcc_lo, v21, 3
	v_fmac_f32_e32 v10, s20, v83
	v_fmac_f32_e32 v11, s21, v83
	v_fmac_f32_e32 v66, vcc_lo, v83
	v_readlane_b32 s20, v14, 3
	v_readlane_b32 s21, v18, 3
	v_readlane_b32 vcc_lo, v22, 3
	v_fmac_f32_e32 v10, s20, v84
	v_fmac_f32_e32 v11, s21, v84
	v_fmac_f32_e32 v66, vcc_lo, v84
	v_readlane_b32 s20, v15, 3
	v_readlane_b32 s21, v19, 3
	v_readlane_b32 vcc_lo, v23, 3
	v_fmac_f32_e32 v10, s20, v85
	v_fmac_f32_e32 v11, s21, v85
	v_fmac_f32_e32 v66, vcc_lo, v85
	global_load_dword v70, v[56:57], off
	v_lshl_add_u64 v[56:57], v[56:57], 0, v[8:9]
	global_load_dword v71, v[56:57], off
	v_lshl_add_u64 v[56:57], v[56:57], 0, v[8:9]
	global_load_dword v72, v[56:57], off
	v_lshl_add_u64 v[56:57], v[56:57], 0, v[8:9]
	global_load_dword v73, v[56:57], off
	v_lshl_add_u64 v[56:57], v[56:57], 0, v[8:9]
	global_load_dword v74, v[56:57], off
	v_lshl_add_u64 v[56:57], v[56:57], 0, v[8:9]
	global_load_dword v75, v[56:57], off
	v_lshl_add_u64 v[56:57], v[56:57], 0, v[8:9]
	global_load_dword v76, v[56:57], off
	v_lshl_add_u64 v[56:57], v[56:57], 0, v[8:9]
	global_load_dword v77, v[56:57], off
	v_lshl_add_u64 v[56:57], v[56:57], 0, v[8:9]
	global_load_dword v78, v[56:57], off
	v_lshl_add_u64 v[56:57], v[56:57], 0, v[8:9]
	global_load_dword v79, v[56:57], off
	v_lshl_add_u64 v[56:57], v[56:57], 0, v[8:9]
	global_load_dword v80, v[56:57], off
	v_lshl_add_u64 v[56:57], v[56:57], 0, v[8:9]
	global_load_dword v81, v[56:57], off
	v_lshl_add_u64 v[56:57], v[56:57], 0, v[8:9]
	global_load_dword v82, v[56:57], off
	v_lshl_add_u64 v[56:57], v[56:57], 0, v[8:9]
	global_load_dword v83, v[56:57], off
	v_lshl_add_u64 v[56:57], v[56:57], 0, v[8:9]
	global_load_dword v84, v[56:57], off
	v_lshl_add_u64 v[56:57], v[56:57], 0, v[8:9]
	global_load_dword v85, v[56:57], off
	v_lshl_add_u64 v[56:57], v[56:57], 0, v[8:9]
	s_waitcnt vmcnt(48)
	v_readlane_b32 s20, v12, 4
	v_readlane_b32 s21, v16, 4
	v_readlane_b32 vcc_lo, v20, 4
	v_fmac_f32_e32 v10, s20, v86
	v_fmac_f32_e32 v11, s21, v86
	v_fmac_f32_e32 v66, vcc_lo, v86
	v_readlane_b32 s20, v13, 4
	v_readlane_b32 s21, v17, 4
	v_readlane_b32 vcc_lo, v21, 4
	v_fmac_f32_e32 v10, s20, v87
	v_fmac_f32_e32 v11, s21, v87
	v_fmac_f32_e32 v66, vcc_lo, v87
	v_readlane_b32 s20, v14, 4
	v_readlane_b32 s21, v18, 4
	v_readlane_b32 vcc_lo, v22, 4
	v_fmac_f32_e32 v10, s20, v88
	v_fmac_f32_e32 v11, s21, v88
	v_fmac_f32_e32 v66, vcc_lo, v88
	v_readlane_b32 s20, v15, 4
	v_readlane_b32 s21, v19, 4
	v_readlane_b32 vcc_lo, v23, 4
	v_fmac_f32_e32 v10, s20, v89
	v_fmac_f32_e32 v11, s21, v89
	v_fmac_f32_e32 v66, vcc_lo, v89
	v_readlane_b32 s20, v12, 5
	v_readlane_b32 s21, v16, 5
	v_readlane_b32 vcc_lo, v20, 5
	v_fmac_f32_e32 v10, s20, v90
	v_fmac_f32_e32 v11, s21, v90
	v_fmac_f32_e32 v66, vcc_lo, v90
	v_readlane_b32 s20, v13, 5
	v_readlane_b32 s21, v17, 5
	v_readlane_b32 vcc_lo, v21, 5
	v_fmac_f32_e32 v10, s20, v91
	v_fmac_f32_e32 v11, s21, v91
	v_fmac_f32_e32 v66, vcc_lo, v91
	v_readlane_b32 s20, v14, 5
	v_readlane_b32 s21, v18, 5
	v_readlane_b32 vcc_lo, v22, 5
	v_fmac_f32_e32 v10, s20, v92
	v_fmac_f32_e32 v11, s21, v92
	v_fmac_f32_e32 v66, vcc_lo, v92
	v_readlane_b32 s20, v15, 5
	v_readlane_b32 s21, v19, 5
	v_readlane_b32 vcc_lo, v23, 5
	v_fmac_f32_e32 v10, s20, v93
	v_fmac_f32_e32 v11, s21, v93
	v_fmac_f32_e32 v66, vcc_lo, v93
	v_readlane_b32 s20, v12, 6
	v_readlane_b32 s21, v16, 6
	v_readlane_b32 vcc_lo, v20, 6
	v_fmac_f32_e32 v10, s20, v94
	v_fmac_f32_e32 v11, s21, v94
	v_fmac_f32_e32 v66, vcc_lo, v94
	v_readlane_b32 s20, v13, 6
	v_readlane_b32 s21, v17, 6
	v_readlane_b32 vcc_lo, v21, 6
	v_fmac_f32_e32 v10, s20, v95
	v_fmac_f32_e32 v11, s21, v95
	v_fmac_f32_e32 v66, vcc_lo, v95
	v_readlane_b32 s20, v14, 6
	v_readlane_b32 s21, v18, 6
	v_readlane_b32 vcc_lo, v22, 6
	v_fmac_f32_e32 v10, s20, v96
	v_fmac_f32_e32 v11, s21, v96
	v_fmac_f32_e32 v66, vcc_lo, v96
	v_readlane_b32 s20, v15, 6
	v_readlane_b32 s21, v19, 6
	v_readlane_b32 vcc_lo, v23, 6
	v_fmac_f32_e32 v10, s20, v97
	v_fmac_f32_e32 v11, s21, v97
	v_fmac_f32_e32 v66, vcc_lo, v97
	v_readlane_b32 s20, v12, 7
	v_readlane_b32 s21, v16, 7
	v_readlane_b32 vcc_lo, v20, 7
	v_fmac_f32_e32 v10, s20, v98
	v_fmac_f32_e32 v11, s21, v98
	v_fmac_f32_e32 v66, vcc_lo, v98
	v_readlane_b32 s20, v13, 7
	v_readlane_b32 s21, v17, 7
	v_readlane_b32 vcc_lo, v21, 7
	v_fmac_f32_e32 v10, s20, v99
	v_fmac_f32_e32 v11, s21, v99
	v_fmac_f32_e32 v66, vcc_lo, v99
	v_readlane_b32 s20, v14, 7
	v_readlane_b32 s21, v18, 7
	v_readlane_b32 vcc_lo, v22, 7
	v_fmac_f32_e32 v10, s20, v100
	v_fmac_f32_e32 v11, s21, v100
	v_fmac_f32_e32 v66, vcc_lo, v100
	v_readlane_b32 s20, v15, 7
	v_readlane_b32 s21, v19, 7
	v_readlane_b32 vcc_lo, v23, 7
	v_fmac_f32_e32 v10, s20, v101
	v_fmac_f32_e32 v11, s21, v101
	v_fmac_f32_e32 v66, vcc_lo, v101
	global_load_dword v86, v[56:57], off
	v_lshl_add_u64 v[56:57], v[56:57], 0, v[8:9]
	global_load_dword v87, v[56:57], off
	v_lshl_add_u64 v[56:57], v[56:57], 0, v[8:9]
	global_load_dword v88, v[56:57], off
	v_lshl_add_u64 v[56:57], v[56:57], 0, v[8:9]
	global_load_dword v89, v[56:57], off
	v_lshl_add_u64 v[56:57], v[56:57], 0, v[8:9]
	global_load_dword v90, v[56:57], off
	v_lshl_add_u64 v[56:57], v[56:57], 0, v[8:9]
	global_load_dword v91, v[56:57], off
	v_lshl_add_u64 v[56:57], v[56:57], 0, v[8:9]
	global_load_dword v92, v[56:57], off
	v_lshl_add_u64 v[56:57], v[56:57], 0, v[8:9]
	global_load_dword v93, v[56:57], off
	v_lshl_add_u64 v[56:57], v[56:57], 0, v[8:9]
	global_load_dword v94, v[56:57], off
	v_lshl_add_u64 v[56:57], v[56:57], 0, v[8:9]
	global_load_dword v95, v[56:57], off
	v_lshl_add_u64 v[56:57], v[56:57], 0, v[8:9]
	global_load_dword v96, v[56:57], off
	v_lshl_add_u64 v[56:57], v[56:57], 0, v[8:9]
	global_load_dword v97, v[56:57], off
	v_lshl_add_u64 v[56:57], v[56:57], 0, v[8:9]
	global_load_dword v98, v[56:57], off
	v_lshl_add_u64 v[56:57], v[56:57], 0, v[8:9]
	global_load_dword v99, v[56:57], off
	v_lshl_add_u64 v[56:57], v[56:57], 0, v[8:9]
	global_load_dword v100, v[56:57], off
	v_lshl_add_u64 v[56:57], v[56:57], 0, v[8:9]
	global_load_dword v101, v[56:57], off
	v_lshl_add_u64 v[56:57], v[56:57], 0, v[8:9]
	s_waitcnt vmcnt(48)
	v_readlane_b32 s20, v12, 8
	v_readlane_b32 s21, v16, 8
	v_readlane_b32 vcc_lo, v20, 8
	v_fmac_f32_e32 v10, s20, v102
	v_fmac_f32_e32 v11, s21, v102
	v_fmac_f32_e32 v66, vcc_lo, v102
	v_readlane_b32 s20, v13, 8
	v_readlane_b32 s21, v17, 8
	v_readlane_b32 vcc_lo, v21, 8
	v_fmac_f32_e32 v10, s20, v103
	v_fmac_f32_e32 v11, s21, v103
	v_fmac_f32_e32 v66, vcc_lo, v103
	v_readlane_b32 s20, v14, 8
	v_readlane_b32 s21, v18, 8
	v_readlane_b32 vcc_lo, v22, 8
	v_fmac_f32_e32 v10, s20, v104
	v_fmac_f32_e32 v11, s21, v104
	v_fmac_f32_e32 v66, vcc_lo, v104
	v_readlane_b32 s20, v15, 8
	v_readlane_b32 s21, v19, 8
	v_readlane_b32 vcc_lo, v23, 8
	v_fmac_f32_e32 v10, s20, v105
	v_fmac_f32_e32 v11, s21, v105
	v_fmac_f32_e32 v66, vcc_lo, v105
	v_readlane_b32 s20, v12, 9
	v_readlane_b32 s21, v16, 9
	v_readlane_b32 vcc_lo, v20, 9
	v_fmac_f32_e32 v10, s20, v106
	v_fmac_f32_e32 v11, s21, v106
	v_fmac_f32_e32 v66, vcc_lo, v106
	v_readlane_b32 s20, v13, 9
	v_readlane_b32 s21, v17, 9
	v_readlane_b32 vcc_lo, v21, 9
	v_fmac_f32_e32 v10, s20, v107
	v_fmac_f32_e32 v11, s21, v107
	v_fmac_f32_e32 v66, vcc_lo, v107
	v_readlane_b32 s20, v14, 9
	v_readlane_b32 s21, v18, 9
	v_readlane_b32 vcc_lo, v22, 9
	v_fmac_f32_e32 v10, s20, v108
	v_fmac_f32_e32 v11, s21, v108
	v_fmac_f32_e32 v66, vcc_lo, v108
	v_readlane_b32 s20, v15, 9
	v_readlane_b32 s21, v19, 9
	v_readlane_b32 vcc_lo, v23, 9
	v_fmac_f32_e32 v10, s20, v109
	v_fmac_f32_e32 v11, s21, v109
	v_fmac_f32_e32 v66, vcc_lo, v109
	v_readlane_b32 s20, v12, 10
	v_readlane_b32 s21, v16, 10
	v_readlane_b32 vcc_lo, v20, 10
	v_fmac_f32_e32 v10, s20, v110
	v_fmac_f32_e32 v11, s21, v110
	v_fmac_f32_e32 v66, vcc_lo, v110
	v_readlane_b32 s20, v13, 10
	v_readlane_b32 s21, v17, 10
	v_readlane_b32 vcc_lo, v21, 10
	v_fmac_f32_e32 v10, s20, v111
	v_fmac_f32_e32 v11, s21, v111
	v_fmac_f32_e32 v66, vcc_lo, v111
	v_readlane_b32 s20, v14, 10
	v_readlane_b32 s21, v18, 10
	v_readlane_b32 vcc_lo, v22, 10
	v_fmac_f32_e32 v10, s20, v112
	v_fmac_f32_e32 v11, s21, v112
	v_fmac_f32_e32 v66, vcc_lo, v112
	v_readlane_b32 s20, v15, 10
	v_readlane_b32 s21, v19, 10
	v_readlane_b32 vcc_lo, v23, 10
	v_fmac_f32_e32 v10, s20, v113
	v_fmac_f32_e32 v11, s21, v113
	v_fmac_f32_e32 v66, vcc_lo, v113
	v_readlane_b32 s20, v12, 11
	v_readlane_b32 s21, v16, 11
	v_readlane_b32 vcc_lo, v20, 11
	v_fmac_f32_e32 v10, s20, v114
	v_fmac_f32_e32 v11, s21, v114
	v_fmac_f32_e32 v66, vcc_lo, v114
	v_readlane_b32 s20, v13, 11
	v_readlane_b32 s21, v17, 11
	v_readlane_b32 vcc_lo, v21, 11
	v_fmac_f32_e32 v10, s20, v115
	v_fmac_f32_e32 v11, s21, v115
	v_fmac_f32_e32 v66, vcc_lo, v115
	v_readlane_b32 s20, v14, 11
	v_readlane_b32 s21, v18, 11
	v_readlane_b32 vcc_lo, v22, 11
	v_fmac_f32_e32 v10, s20, v116
	v_fmac_f32_e32 v11, s21, v116
	v_fmac_f32_e32 v66, vcc_lo, v116
	v_readlane_b32 s20, v15, 11
	v_readlane_b32 s21, v19, 11
	v_readlane_b32 vcc_lo, v23, 11
	v_fmac_f32_e32 v10, s20, v117
	v_fmac_f32_e32 v11, s21, v117
	v_fmac_f32_e32 v66, vcc_lo, v117
	global_load_dword v102, v[56:57], off
	v_lshl_add_u64 v[56:57], v[56:57], 0, v[8:9]
	global_load_dword v103, v[56:57], off
	v_lshl_add_u64 v[56:57], v[56:57], 0, v[8:9]
	global_load_dword v104, v[56:57], off
	v_lshl_add_u64 v[56:57], v[56:57], 0, v[8:9]
	global_load_dword v105, v[56:57], off
	v_lshl_add_u64 v[56:57], v[56:57], 0, v[8:9]
	global_load_dword v106, v[56:57], off
	v_lshl_add_u64 v[56:57], v[56:57], 0, v[8:9]
	global_load_dword v107, v[56:57], off
	v_lshl_add_u64 v[56:57], v[56:57], 0, v[8:9]
	global_load_dword v108, v[56:57], off
	v_lshl_add_u64 v[56:57], v[56:57], 0, v[8:9]
	global_load_dword v109, v[56:57], off
	v_lshl_add_u64 v[56:57], v[56:57], 0, v[8:9]
	global_load_dword v110, v[56:57], off
	v_lshl_add_u64 v[56:57], v[56:57], 0, v[8:9]
	global_load_dword v111, v[56:57], off
	v_lshl_add_u64 v[56:57], v[56:57], 0, v[8:9]
	global_load_dword v112, v[56:57], off
	v_lshl_add_u64 v[56:57], v[56:57], 0, v[8:9]
	global_load_dword v113, v[56:57], off
	v_lshl_add_u64 v[56:57], v[56:57], 0, v[8:9]
	global_load_dword v114, v[56:57], off
	v_lshl_add_u64 v[56:57], v[56:57], 0, v[8:9]
	global_load_dword v115, v[56:57], off
	v_lshl_add_u64 v[56:57], v[56:57], 0, v[8:9]
	global_load_dword v116, v[56:57], off
	v_lshl_add_u64 v[56:57], v[56:57], 0, v[8:9]
	global_load_dword v117, v[56:57], off
	v_lshl_add_u64 v[56:57], v[56:57], 0, v[8:9]
	s_waitcnt vmcnt(48)
	v_readlane_b32 s20, v12, 12
	v_readlane_b32 s21, v16, 12
	v_readlane_b32 vcc_lo, v20, 12
	v_fmac_f32_e32 v10, s20, v118
	v_fmac_f32_e32 v11, s21, v118
	v_fmac_f32_e32 v66, vcc_lo, v118
	v_readlane_b32 s20, v13, 12
	v_readlane_b32 s21, v17, 12
	v_readlane_b32 vcc_lo, v21, 12
	v_fmac_f32_e32 v10, s20, v119
	v_fmac_f32_e32 v11, s21, v119
	v_fmac_f32_e32 v66, vcc_lo, v119
	v_readlane_b32 s20, v14, 12
	v_readlane_b32 s21, v18, 12
	v_readlane_b32 vcc_lo, v22, 12
	v_fmac_f32_e32 v10, s20, v120
	v_fmac_f32_e32 v11, s21, v120
	v_fmac_f32_e32 v66, vcc_lo, v120
	v_readlane_b32 s20, v15, 12
	v_readlane_b32 s21, v19, 12
	v_readlane_b32 vcc_lo, v23, 12
	v_fmac_f32_e32 v10, s20, v121
	v_fmac_f32_e32 v11, s21, v121
	v_fmac_f32_e32 v66, vcc_lo, v121
	v_readlane_b32 s20, v12, 13
	v_readlane_b32 s21, v16, 13
	v_readlane_b32 vcc_lo, v20, 13
	v_fmac_f32_e32 v10, s20, v122
	v_fmac_f32_e32 v11, s21, v122
	v_fmac_f32_e32 v66, vcc_lo, v122
	v_readlane_b32 s20, v13, 13
	v_readlane_b32 s21, v17, 13
	v_readlane_b32 vcc_lo, v21, 13
	v_fmac_f32_e32 v10, s20, v123
	v_fmac_f32_e32 v11, s21, v123
	v_fmac_f32_e32 v66, vcc_lo, v123
	v_readlane_b32 s20, v14, 13
	v_readlane_b32 s21, v18, 13
	v_readlane_b32 vcc_lo, v22, 13
	v_fmac_f32_e32 v10, s20, v124
	v_fmac_f32_e32 v11, s21, v124
	v_fmac_f32_e32 v66, vcc_lo, v124
	v_readlane_b32 s20, v15, 13
	v_readlane_b32 s21, v19, 13
	v_readlane_b32 vcc_lo, v23, 13
	v_fmac_f32_e32 v10, s20, v125
	v_fmac_f32_e32 v11, s21, v125
	v_fmac_f32_e32 v66, vcc_lo, v125
	v_readlane_b32 s20, v12, 14
	v_readlane_b32 s21, v16, 14
	v_readlane_b32 vcc_lo, v20, 14
	v_fmac_f32_e32 v10, s20, v126
	v_fmac_f32_e32 v11, s21, v126
	v_fmac_f32_e32 v66, vcc_lo, v126
	v_readlane_b32 s20, v13, 14
	v_readlane_b32 s21, v17, 14
	v_readlane_b32 vcc_lo, v21, 14
	v_fmac_f32_e32 v10, s20, v127
	v_fmac_f32_e32 v11, s21, v127
	v_fmac_f32_e32 v66, vcc_lo, v127
	v_readlane_b32 s20, v14, 14
	v_readlane_b32 s21, v18, 14
	v_readlane_b32 vcc_lo, v22, 14
	v_fmac_f32_e32 v10, s20, v128
	v_fmac_f32_e32 v11, s21, v128
	v_fmac_f32_e32 v66, vcc_lo, v128
	v_readlane_b32 s20, v15, 14
	v_readlane_b32 s21, v19, 14
	v_readlane_b32 vcc_lo, v23, 14
	v_fmac_f32_e32 v10, s20, v129
	v_fmac_f32_e32 v11, s21, v129
	v_fmac_f32_e32 v66, vcc_lo, v129
	v_readlane_b32 s20, v12, 15
	v_readlane_b32 s21, v16, 15
	v_readlane_b32 vcc_lo, v20, 15
	v_fmac_f32_e32 v10, s20, v130
	v_fmac_f32_e32 v11, s21, v130
	v_fmac_f32_e32 v66, vcc_lo, v130
	v_readlane_b32 s20, v13, 15
	v_readlane_b32 s21, v17, 15
	v_readlane_b32 vcc_lo, v21, 15
	v_fmac_f32_e32 v10, s20, v131
	v_fmac_f32_e32 v11, s21, v131
	v_fmac_f32_e32 v66, vcc_lo, v131
	v_readlane_b32 s20, v14, 15
	v_readlane_b32 s21, v18, 15
	v_readlane_b32 vcc_lo, v22, 15
	v_fmac_f32_e32 v10, s20, v132
	v_fmac_f32_e32 v11, s21, v132
	v_fmac_f32_e32 v66, vcc_lo, v132
	v_readlane_b32 s20, v15, 15
	v_readlane_b32 s21, v19, 15
	v_readlane_b32 vcc_lo, v23, 15
	v_fmac_f32_e32 v10, s20, v133
	v_fmac_f32_e32 v11, s21, v133
	v_fmac_f32_e32 v66, vcc_lo, v133
	global_load_dword v118, v[56:57], off
	v_lshl_add_u64 v[56:57], v[56:57], 0, v[8:9]
	global_load_dword v119, v[56:57], off
	v_lshl_add_u64 v[56:57], v[56:57], 0, v[8:9]
	global_load_dword v120, v[56:57], off
	v_lshl_add_u64 v[56:57], v[56:57], 0, v[8:9]
	global_load_dword v121, v[56:57], off
	v_lshl_add_u64 v[56:57], v[56:57], 0, v[8:9]
	global_load_dword v122, v[56:57], off
	v_lshl_add_u64 v[56:57], v[56:57], 0, v[8:9]
	global_load_dword v123, v[56:57], off
	v_lshl_add_u64 v[56:57], v[56:57], 0, v[8:9]
	global_load_dword v124, v[56:57], off
	v_lshl_add_u64 v[56:57], v[56:57], 0, v[8:9]
	global_load_dword v125, v[56:57], off
	v_lshl_add_u64 v[56:57], v[56:57], 0, v[8:9]
	global_load_dword v126, v[56:57], off
	v_lshl_add_u64 v[56:57], v[56:57], 0, v[8:9]
	global_load_dword v127, v[56:57], off
	v_lshl_add_u64 v[56:57], v[56:57], 0, v[8:9]
	global_load_dword v128, v[56:57], off
	v_lshl_add_u64 v[56:57], v[56:57], 0, v[8:9]
	global_load_dword v129, v[56:57], off
	v_lshl_add_u64 v[56:57], v[56:57], 0, v[8:9]
	global_load_dword v130, v[56:57], off
	v_lshl_add_u64 v[56:57], v[56:57], 0, v[8:9]
	global_load_dword v131, v[56:57], off
	v_lshl_add_u64 v[56:57], v[56:57], 0, v[8:9]
	global_load_dword v132, v[56:57], off
	v_lshl_add_u64 v[56:57], v[56:57], 0, v[8:9]
	global_load_dword v133, v[56:57], off
	v_lshl_add_u64 v[56:57], v[56:57], 0, v[8:9]
	s_waitcnt vmcnt(48)
	v_readlane_b32 s20, v12, 16
	v_readlane_b32 s21, v16, 16
	v_readlane_b32 vcc_lo, v20, 16
	v_fmac_f32_e32 v10, s20, v70
	v_fmac_f32_e32 v11, s21, v70
	v_fmac_f32_e32 v66, vcc_lo, v70
	v_readlane_b32 s20, v13, 16
	v_readlane_b32 s21, v17, 16
	v_readlane_b32 vcc_lo, v21, 16
	v_fmac_f32_e32 v10, s20, v71
	v_fmac_f32_e32 v11, s21, v71
	v_fmac_f32_e32 v66, vcc_lo, v71
	v_readlane_b32 s20, v14, 16
	v_readlane_b32 s21, v18, 16
	v_readlane_b32 vcc_lo, v22, 16
	v_fmac_f32_e32 v10, s20, v72
	v_fmac_f32_e32 v11, s21, v72
	v_fmac_f32_e32 v66, vcc_lo, v72
	v_readlane_b32 s20, v15, 16
	v_readlane_b32 s21, v19, 16
	v_readlane_b32 vcc_lo, v23, 16
	v_fmac_f32_e32 v10, s20, v73
	v_fmac_f32_e32 v11, s21, v73
	v_fmac_f32_e32 v66, vcc_lo, v73
	v_readlane_b32 s20, v12, 17
	v_readlane_b32 s21, v16, 17
	v_readlane_b32 vcc_lo, v20, 17
	v_fmac_f32_e32 v10, s20, v74
	v_fmac_f32_e32 v11, s21, v74
	v_fmac_f32_e32 v66, vcc_lo, v74
	v_readlane_b32 s20, v13, 17
	v_readlane_b32 s21, v17, 17
	v_readlane_b32 vcc_lo, v21, 17
	v_fmac_f32_e32 v10, s20, v75
	v_fmac_f32_e32 v11, s21, v75
	v_fmac_f32_e32 v66, vcc_lo, v75
	v_readlane_b32 s20, v14, 17
	v_readlane_b32 s21, v18, 17
	v_readlane_b32 vcc_lo, v22, 17
	v_fmac_f32_e32 v10, s20, v76
	v_fmac_f32_e32 v11, s21, v76
	v_fmac_f32_e32 v66, vcc_lo, v76
	v_readlane_b32 s20, v15, 17
	v_readlane_b32 s21, v19, 17
	v_readlane_b32 vcc_lo, v23, 17
	v_fmac_f32_e32 v10, s20, v77
	v_fmac_f32_e32 v11, s21, v77
	v_fmac_f32_e32 v66, vcc_lo, v77
	v_readlane_b32 s20, v12, 18
	v_readlane_b32 s21, v16, 18
	v_readlane_b32 vcc_lo, v20, 18
	v_fmac_f32_e32 v10, s20, v78
	v_fmac_f32_e32 v11, s21, v78
	v_fmac_f32_e32 v66, vcc_lo, v78
	v_readlane_b32 s20, v13, 18
	v_readlane_b32 s21, v17, 18
	v_readlane_b32 vcc_lo, v21, 18
	v_fmac_f32_e32 v10, s20, v79
	v_fmac_f32_e32 v11, s21, v79
	v_fmac_f32_e32 v66, vcc_lo, v79
	v_readlane_b32 s20, v14, 18
	v_readlane_b32 s21, v18, 18
	v_readlane_b32 vcc_lo, v22, 18
	v_fmac_f32_e32 v10, s20, v80
	v_fmac_f32_e32 v11, s21, v80
	v_fmac_f32_e32 v66, vcc_lo, v80
	v_readlane_b32 s20, v15, 18
	v_readlane_b32 s21, v19, 18
	v_readlane_b32 vcc_lo, v23, 18
	v_fmac_f32_e32 v10, s20, v81
	v_fmac_f32_e32 v11, s21, v81
	v_fmac_f32_e32 v66, vcc_lo, v81
	v_readlane_b32 s20, v12, 19
	v_readlane_b32 s21, v16, 19
	v_readlane_b32 vcc_lo, v20, 19
	v_fmac_f32_e32 v10, s20, v82
	v_fmac_f32_e32 v11, s21, v82
	v_fmac_f32_e32 v66, vcc_lo, v82
	v_readlane_b32 s20, v13, 19
	v_readlane_b32 s21, v17, 19
	v_readlane_b32 vcc_lo, v21, 19
	v_fmac_f32_e32 v10, s20, v83
	v_fmac_f32_e32 v11, s21, v83
	v_fmac_f32_e32 v66, vcc_lo, v83
	v_readlane_b32 s20, v14, 19
	v_readlane_b32 s21, v18, 19
	v_readlane_b32 vcc_lo, v22, 19
	v_fmac_f32_e32 v10, s20, v84
	v_fmac_f32_e32 v11, s21, v84
	v_fmac_f32_e32 v66, vcc_lo, v84
	v_readlane_b32 s20, v15, 19
	v_readlane_b32 s21, v19, 19
	v_readlane_b32 vcc_lo, v23, 19
	v_fmac_f32_e32 v10, s20, v85
	v_fmac_f32_e32 v11, s21, v85
	v_fmac_f32_e32 v66, vcc_lo, v85
	global_load_dword v70, v[56:57], off
	v_lshl_add_u64 v[56:57], v[56:57], 0, v[8:9]
	global_load_dword v71, v[56:57], off
	v_lshl_add_u64 v[56:57], v[56:57], 0, v[8:9]
	global_load_dword v72, v[56:57], off
	v_lshl_add_u64 v[56:57], v[56:57], 0, v[8:9]
	global_load_dword v73, v[56:57], off
	v_lshl_add_u64 v[56:57], v[56:57], 0, v[8:9]
	global_load_dword v74, v[56:57], off
	v_lshl_add_u64 v[56:57], v[56:57], 0, v[8:9]
	global_load_dword v75, v[56:57], off
	v_lshl_add_u64 v[56:57], v[56:57], 0, v[8:9]
	global_load_dword v76, v[56:57], off
	v_lshl_add_u64 v[56:57], v[56:57], 0, v[8:9]
	global_load_dword v77, v[56:57], off
	v_lshl_add_u64 v[56:57], v[56:57], 0, v[8:9]
	global_load_dword v78, v[56:57], off
	v_lshl_add_u64 v[56:57], v[56:57], 0, v[8:9]
	global_load_dword v79, v[56:57], off
	v_lshl_add_u64 v[56:57], v[56:57], 0, v[8:9]
	global_load_dword v80, v[56:57], off
	v_lshl_add_u64 v[56:57], v[56:57], 0, v[8:9]
	global_load_dword v81, v[56:57], off
	v_lshl_add_u64 v[56:57], v[56:57], 0, v[8:9]
	global_load_dword v82, v[56:57], off
	v_lshl_add_u64 v[56:57], v[56:57], 0, v[8:9]
	global_load_dword v83, v[56:57], off
	v_lshl_add_u64 v[56:57], v[56:57], 0, v[8:9]
	global_load_dword v84, v[56:57], off
	v_lshl_add_u64 v[56:57], v[56:57], 0, v[8:9]
	global_load_dword v85, v[56:57], off
	v_lshl_add_u64 v[56:57], v[56:57], 0, v[8:9]
	s_waitcnt vmcnt(48)
	v_readlane_b32 s20, v12, 20
	v_readlane_b32 s21, v16, 20
	v_readlane_b32 vcc_lo, v20, 20
	v_fmac_f32_e32 v10, s20, v86
	v_fmac_f32_e32 v11, s21, v86
	v_fmac_f32_e32 v66, vcc_lo, v86
	v_readlane_b32 s20, v13, 20
	v_readlane_b32 s21, v17, 20
	v_readlane_b32 vcc_lo, v21, 20
	v_fmac_f32_e32 v10, s20, v87
	v_fmac_f32_e32 v11, s21, v87
	v_fmac_f32_e32 v66, vcc_lo, v87
	v_readlane_b32 s20, v14, 20
	v_readlane_b32 s21, v18, 20
	v_readlane_b32 vcc_lo, v22, 20
	v_fmac_f32_e32 v10, s20, v88
	v_fmac_f32_e32 v11, s21, v88
	v_fmac_f32_e32 v66, vcc_lo, v88
	v_readlane_b32 s20, v15, 20
	v_readlane_b32 s21, v19, 20
	v_readlane_b32 vcc_lo, v23, 20
	v_fmac_f32_e32 v10, s20, v89
	v_fmac_f32_e32 v11, s21, v89
	v_fmac_f32_e32 v66, vcc_lo, v89
	v_readlane_b32 s20, v12, 21
	v_readlane_b32 s21, v16, 21
	v_readlane_b32 vcc_lo, v20, 21
	v_fmac_f32_e32 v10, s20, v90
	v_fmac_f32_e32 v11, s21, v90
	v_fmac_f32_e32 v66, vcc_lo, v90
	v_readlane_b32 s20, v13, 21
	v_readlane_b32 s21, v17, 21
	v_readlane_b32 vcc_lo, v21, 21
	v_fmac_f32_e32 v10, s20, v91
	v_fmac_f32_e32 v11, s21, v91
	v_fmac_f32_e32 v66, vcc_lo, v91
	v_readlane_b32 s20, v14, 21
	v_readlane_b32 s21, v18, 21
	v_readlane_b32 vcc_lo, v22, 21
	v_fmac_f32_e32 v10, s20, v92
	v_fmac_f32_e32 v11, s21, v92
	v_fmac_f32_e32 v66, vcc_lo, v92
	v_readlane_b32 s20, v15, 21
	v_readlane_b32 s21, v19, 21
	v_readlane_b32 vcc_lo, v23, 21
	v_fmac_f32_e32 v10, s20, v93
	v_fmac_f32_e32 v11, s21, v93
	v_fmac_f32_e32 v66, vcc_lo, v93
	v_readlane_b32 s20, v12, 22
	v_readlane_b32 s21, v16, 22
	v_readlane_b32 vcc_lo, v20, 22
	v_fmac_f32_e32 v10, s20, v94
	v_fmac_f32_e32 v11, s21, v94
	v_fmac_f32_e32 v66, vcc_lo, v94
	v_readlane_b32 s20, v13, 22
	v_readlane_b32 s21, v17, 22
	v_readlane_b32 vcc_lo, v21, 22
	v_fmac_f32_e32 v10, s20, v95
	v_fmac_f32_e32 v11, s21, v95
	v_fmac_f32_e32 v66, vcc_lo, v95
	v_readlane_b32 s20, v14, 22
	v_readlane_b32 s21, v18, 22
	v_readlane_b32 vcc_lo, v22, 22
	v_fmac_f32_e32 v10, s20, v96
	v_fmac_f32_e32 v11, s21, v96
	v_fmac_f32_e32 v66, vcc_lo, v96
	v_readlane_b32 s20, v15, 22
	v_readlane_b32 s21, v19, 22
	v_readlane_b32 vcc_lo, v23, 22
	v_fmac_f32_e32 v10, s20, v97
	v_fmac_f32_e32 v11, s21, v97
	v_fmac_f32_e32 v66, vcc_lo, v97
	v_readlane_b32 s20, v12, 23
	v_readlane_b32 s21, v16, 23
	v_readlane_b32 vcc_lo, v20, 23
	v_fmac_f32_e32 v10, s20, v98
	v_fmac_f32_e32 v11, s21, v98
	v_fmac_f32_e32 v66, vcc_lo, v98
	v_readlane_b32 s20, v13, 23
	v_readlane_b32 s21, v17, 23
	v_readlane_b32 vcc_lo, v21, 23
	v_fmac_f32_e32 v10, s20, v99
	v_fmac_f32_e32 v11, s21, v99
	v_fmac_f32_e32 v66, vcc_lo, v99
	v_readlane_b32 s20, v14, 23
	v_readlane_b32 s21, v18, 23
	v_readlane_b32 vcc_lo, v22, 23
	v_fmac_f32_e32 v10, s20, v100
	v_fmac_f32_e32 v11, s21, v100
	v_fmac_f32_e32 v66, vcc_lo, v100
	v_readlane_b32 s20, v15, 23
	v_readlane_b32 s21, v19, 23
	v_readlane_b32 vcc_lo, v23, 23
	v_fmac_f32_e32 v10, s20, v101
	v_fmac_f32_e32 v11, s21, v101
	v_fmac_f32_e32 v66, vcc_lo, v101
	global_load_dword v86, v[56:57], off
	v_lshl_add_u64 v[56:57], v[56:57], 0, v[8:9]
	global_load_dword v87, v[56:57], off
	v_lshl_add_u64 v[56:57], v[56:57], 0, v[8:9]
	global_load_dword v88, v[56:57], off
	v_lshl_add_u64 v[56:57], v[56:57], 0, v[8:9]
	global_load_dword v89, v[56:57], off
	v_lshl_add_u64 v[56:57], v[56:57], 0, v[8:9]
	global_load_dword v90, v[56:57], off
	v_lshl_add_u64 v[56:57], v[56:57], 0, v[8:9]
	global_load_dword v91, v[56:57], off
	v_lshl_add_u64 v[56:57], v[56:57], 0, v[8:9]
	global_load_dword v92, v[56:57], off
	v_lshl_add_u64 v[56:57], v[56:57], 0, v[8:9]
	global_load_dword v93, v[56:57], off
	v_lshl_add_u64 v[56:57], v[56:57], 0, v[8:9]
	global_load_dword v94, v[56:57], off
	v_lshl_add_u64 v[56:57], v[56:57], 0, v[8:9]
	global_load_dword v95, v[56:57], off
	v_lshl_add_u64 v[56:57], v[56:57], 0, v[8:9]
	global_load_dword v96, v[56:57], off
	v_lshl_add_u64 v[56:57], v[56:57], 0, v[8:9]
	global_load_dword v97, v[56:57], off
	v_lshl_add_u64 v[56:57], v[56:57], 0, v[8:9]
	global_load_dword v98, v[56:57], off
	v_lshl_add_u64 v[56:57], v[56:57], 0, v[8:9]
	global_load_dword v99, v[56:57], off
	v_lshl_add_u64 v[56:57], v[56:57], 0, v[8:9]
	global_load_dword v100, v[56:57], off
	v_lshl_add_u64 v[56:57], v[56:57], 0, v[8:9]
	global_load_dword v101, v[56:57], off
	v_lshl_add_u64 v[56:57], v[56:57], 0, v[8:9]
	s_waitcnt vmcnt(48)
	v_readlane_b32 s20, v12, 24
	v_readlane_b32 s21, v16, 24
	v_readlane_b32 vcc_lo, v20, 24
	v_fmac_f32_e32 v10, s20, v102
	v_fmac_f32_e32 v11, s21, v102
	v_fmac_f32_e32 v66, vcc_lo, v102
	v_readlane_b32 s20, v13, 24
	v_readlane_b32 s21, v17, 24
	v_readlane_b32 vcc_lo, v21, 24
	v_fmac_f32_e32 v10, s20, v103
	v_fmac_f32_e32 v11, s21, v103
	v_fmac_f32_e32 v66, vcc_lo, v103
	v_readlane_b32 s20, v14, 24
	v_readlane_b32 s21, v18, 24
	v_readlane_b32 vcc_lo, v22, 24
	v_fmac_f32_e32 v10, s20, v104
	v_fmac_f32_e32 v11, s21, v104
	v_fmac_f32_e32 v66, vcc_lo, v104
	v_readlane_b32 s20, v15, 24
	v_readlane_b32 s21, v19, 24
	v_readlane_b32 vcc_lo, v23, 24
	v_fmac_f32_e32 v10, s20, v105
	v_fmac_f32_e32 v11, s21, v105
	v_fmac_f32_e32 v66, vcc_lo, v105
	v_readlane_b32 s20, v12, 25
	v_readlane_b32 s21, v16, 25
	v_readlane_b32 vcc_lo, v20, 25
	v_fmac_f32_e32 v10, s20, v106
	v_fmac_f32_e32 v11, s21, v106
	v_fmac_f32_e32 v66, vcc_lo, v106
	v_readlane_b32 s20, v13, 25
	v_readlane_b32 s21, v17, 25
	v_readlane_b32 vcc_lo, v21, 25
	v_fmac_f32_e32 v10, s20, v107
	v_fmac_f32_e32 v11, s21, v107
	v_fmac_f32_e32 v66, vcc_lo, v107
	v_readlane_b32 s20, v14, 25
	v_readlane_b32 s21, v18, 25
	v_readlane_b32 vcc_lo, v22, 25
	v_fmac_f32_e32 v10, s20, v108
	v_fmac_f32_e32 v11, s21, v108
	v_fmac_f32_e32 v66, vcc_lo, v108
	v_readlane_b32 s20, v15, 25
	v_readlane_b32 s21, v19, 25
	v_readlane_b32 vcc_lo, v23, 25
	v_fmac_f32_e32 v10, s20, v109
	v_fmac_f32_e32 v11, s21, v109
	v_fmac_f32_e32 v66, vcc_lo, v109
	v_readlane_b32 s20, v12, 26
	v_readlane_b32 s21, v16, 26
	v_readlane_b32 vcc_lo, v20, 26
	v_fmac_f32_e32 v10, s20, v110
	v_fmac_f32_e32 v11, s21, v110
	v_fmac_f32_e32 v66, vcc_lo, v110
	v_readlane_b32 s20, v13, 26
	v_readlane_b32 s21, v17, 26
	v_readlane_b32 vcc_lo, v21, 26
	v_fmac_f32_e32 v10, s20, v111
	v_fmac_f32_e32 v11, s21, v111
	v_fmac_f32_e32 v66, vcc_lo, v111
	v_readlane_b32 s20, v14, 26
	v_readlane_b32 s21, v18, 26
	v_readlane_b32 vcc_lo, v22, 26
	v_fmac_f32_e32 v10, s20, v112
	v_fmac_f32_e32 v11, s21, v112
	v_fmac_f32_e32 v66, vcc_lo, v112
	v_readlane_b32 s20, v15, 26
	v_readlane_b32 s21, v19, 26
	v_readlane_b32 vcc_lo, v23, 26
	v_fmac_f32_e32 v10, s20, v113
	v_fmac_f32_e32 v11, s21, v113
	v_fmac_f32_e32 v66, vcc_lo, v113
	v_readlane_b32 s20, v12, 27
	v_readlane_b32 s21, v16, 27
	v_readlane_b32 vcc_lo, v20, 27
	v_fmac_f32_e32 v10, s20, v114
	v_fmac_f32_e32 v11, s21, v114
	v_fmac_f32_e32 v66, vcc_lo, v114
	v_readlane_b32 s20, v13, 27
	v_readlane_b32 s21, v17, 27
	v_readlane_b32 vcc_lo, v21, 27
	v_fmac_f32_e32 v10, s20, v115
	v_fmac_f32_e32 v11, s21, v115
	v_fmac_f32_e32 v66, vcc_lo, v115
	v_readlane_b32 s20, v14, 27
	v_readlane_b32 s21, v18, 27
	v_readlane_b32 vcc_lo, v22, 27
	v_fmac_f32_e32 v10, s20, v116
	v_fmac_f32_e32 v11, s21, v116
	v_fmac_f32_e32 v66, vcc_lo, v116
	v_readlane_b32 s20, v15, 27
	v_readlane_b32 s21, v19, 27
	v_readlane_b32 vcc_lo, v23, 27
	v_fmac_f32_e32 v10, s20, v117
	v_fmac_f32_e32 v11, s21, v117
	v_fmac_f32_e32 v66, vcc_lo, v117
	global_load_dword v102, v[56:57], off
	v_lshl_add_u64 v[56:57], v[56:57], 0, v[8:9]
	global_load_dword v103, v[56:57], off
	v_lshl_add_u64 v[56:57], v[56:57], 0, v[8:9]
	global_load_dword v104, v[56:57], off
	v_lshl_add_u64 v[56:57], v[56:57], 0, v[8:9]
	global_load_dword v105, v[56:57], off
	v_lshl_add_u64 v[56:57], v[56:57], 0, v[8:9]
	global_load_dword v106, v[56:57], off
	v_lshl_add_u64 v[56:57], v[56:57], 0, v[8:9]
	global_load_dword v107, v[56:57], off
	v_lshl_add_u64 v[56:57], v[56:57], 0, v[8:9]
	global_load_dword v108, v[56:57], off
	v_lshl_add_u64 v[56:57], v[56:57], 0, v[8:9]
	global_load_dword v109, v[56:57], off
	v_lshl_add_u64 v[56:57], v[56:57], 0, v[8:9]
	global_load_dword v110, v[56:57], off
	v_lshl_add_u64 v[56:57], v[56:57], 0, v[8:9]
	global_load_dword v111, v[56:57], off
	v_lshl_add_u64 v[56:57], v[56:57], 0, v[8:9]
	global_load_dword v112, v[56:57], off
	v_lshl_add_u64 v[56:57], v[56:57], 0, v[8:9]
	global_load_dword v113, v[56:57], off
	v_lshl_add_u64 v[56:57], v[56:57], 0, v[8:9]
	global_load_dword v114, v[56:57], off
	v_lshl_add_u64 v[56:57], v[56:57], 0, v[8:9]
	global_load_dword v115, v[56:57], off
	v_lshl_add_u64 v[56:57], v[56:57], 0, v[8:9]
	global_load_dword v116, v[56:57], off
	v_lshl_add_u64 v[56:57], v[56:57], 0, v[8:9]
	global_load_dword v117, v[56:57], off
	v_lshl_add_u64 v[56:57], v[56:57], 0, v[8:9]
	s_waitcnt vmcnt(48)
	v_readlane_b32 s20, v12, 28
	v_readlane_b32 s21, v16, 28
	v_readlane_b32 vcc_lo, v20, 28
	v_fmac_f32_e32 v10, s20, v118
	v_fmac_f32_e32 v11, s21, v118
	v_fmac_f32_e32 v66, vcc_lo, v118
	v_readlane_b32 s20, v13, 28
	v_readlane_b32 s21, v17, 28
	v_readlane_b32 vcc_lo, v21, 28
	v_fmac_f32_e32 v10, s20, v119
	v_fmac_f32_e32 v11, s21, v119
	v_fmac_f32_e32 v66, vcc_lo, v119
	v_readlane_b32 s20, v14, 28
	v_readlane_b32 s21, v18, 28
	v_readlane_b32 vcc_lo, v22, 28
	v_fmac_f32_e32 v10, s20, v120
	v_fmac_f32_e32 v11, s21, v120
	v_fmac_f32_e32 v66, vcc_lo, v120
	v_readlane_b32 s20, v15, 28
	v_readlane_b32 s21, v19, 28
	v_readlane_b32 vcc_lo, v23, 28
	v_fmac_f32_e32 v10, s20, v121
	v_fmac_f32_e32 v11, s21, v121
	v_fmac_f32_e32 v66, vcc_lo, v121
	v_readlane_b32 s20, v12, 29
	v_readlane_b32 s21, v16, 29
	v_readlane_b32 vcc_lo, v20, 29
	v_fmac_f32_e32 v10, s20, v122
	v_fmac_f32_e32 v11, s21, v122
	v_fmac_f32_e32 v66, vcc_lo, v122
	v_readlane_b32 s20, v13, 29
	v_readlane_b32 s21, v17, 29
	v_readlane_b32 vcc_lo, v21, 29
	v_fmac_f32_e32 v10, s20, v123
	v_fmac_f32_e32 v11, s21, v123
	v_fmac_f32_e32 v66, vcc_lo, v123
	v_readlane_b32 s20, v14, 29
	v_readlane_b32 s21, v18, 29
	v_readlane_b32 vcc_lo, v22, 29
	v_fmac_f32_e32 v10, s20, v124
	v_fmac_f32_e32 v11, s21, v124
	v_fmac_f32_e32 v66, vcc_lo, v124
	v_readlane_b32 s20, v15, 29
	v_readlane_b32 s21, v19, 29
	v_readlane_b32 vcc_lo, v23, 29
	v_fmac_f32_e32 v10, s20, v125
	v_fmac_f32_e32 v11, s21, v125
	v_fmac_f32_e32 v66, vcc_lo, v125
	v_readlane_b32 s20, v12, 30
	v_readlane_b32 s21, v16, 30
	v_readlane_b32 vcc_lo, v20, 30
	v_fmac_f32_e32 v10, s20, v126
	v_fmac_f32_e32 v11, s21, v126
	v_fmac_f32_e32 v66, vcc_lo, v126
	v_readlane_b32 s20, v13, 30
	v_readlane_b32 s21, v17, 30
	v_readlane_b32 vcc_lo, v21, 30
	v_fmac_f32_e32 v10, s20, v127
	v_fmac_f32_e32 v11, s21, v127
	v_fmac_f32_e32 v66, vcc_lo, v127
	v_readlane_b32 s20, v14, 30
	v_readlane_b32 s21, v18, 30
	v_readlane_b32 vcc_lo, v22, 30
	v_fmac_f32_e32 v10, s20, v128
	v_fmac_f32_e32 v11, s21, v128
	v_fmac_f32_e32 v66, vcc_lo, v128
	v_readlane_b32 s20, v15, 30
	v_readlane_b32 s21, v19, 30
	v_readlane_b32 vcc_lo, v23, 30
	v_fmac_f32_e32 v10, s20, v129
	v_fmac_f32_e32 v11, s21, v129
	v_fmac_f32_e32 v66, vcc_lo, v129
	v_readlane_b32 s20, v12, 31
	v_readlane_b32 s21, v16, 31
	v_readlane_b32 vcc_lo, v20, 31
	v_fmac_f32_e32 v10, s20, v130
	v_fmac_f32_e32 v11, s21, v130
	v_fmac_f32_e32 v66, vcc_lo, v130
	v_readlane_b32 s20, v13, 31
	v_readlane_b32 s21, v17, 31
	v_readlane_b32 vcc_lo, v21, 31
	v_fmac_f32_e32 v10, s20, v131
	v_fmac_f32_e32 v11, s21, v131
	v_fmac_f32_e32 v66, vcc_lo, v131
	v_readlane_b32 s20, v14, 31
	v_readlane_b32 s21, v18, 31
	v_readlane_b32 vcc_lo, v22, 31
	v_fmac_f32_e32 v10, s20, v132
	v_fmac_f32_e32 v11, s21, v132
	v_fmac_f32_e32 v66, vcc_lo, v132
	v_readlane_b32 s20, v15, 31
	v_readlane_b32 s21, v19, 31
	v_readlane_b32 vcc_lo, v23, 31
	v_fmac_f32_e32 v10, s20, v133
	v_fmac_f32_e32 v11, s21, v133
	v_fmac_f32_e32 v66, vcc_lo, v133
	global_load_dword v118, v[56:57], off
	v_lshl_add_u64 v[56:57], v[56:57], 0, v[8:9]
	global_load_dword v119, v[56:57], off
	v_lshl_add_u64 v[56:57], v[56:57], 0, v[8:9]
	global_load_dword v120, v[56:57], off
	v_lshl_add_u64 v[56:57], v[56:57], 0, v[8:9]
	global_load_dword v121, v[56:57], off
	v_lshl_add_u64 v[56:57], v[56:57], 0, v[8:9]
	global_load_dword v122, v[56:57], off
	v_lshl_add_u64 v[56:57], v[56:57], 0, v[8:9]
	global_load_dword v123, v[56:57], off
	v_lshl_add_u64 v[56:57], v[56:57], 0, v[8:9]
	global_load_dword v124, v[56:57], off
	v_lshl_add_u64 v[56:57], v[56:57], 0, v[8:9]
	global_load_dword v125, v[56:57], off
	v_lshl_add_u64 v[56:57], v[56:57], 0, v[8:9]
	global_load_dword v126, v[56:57], off
	v_lshl_add_u64 v[56:57], v[56:57], 0, v[8:9]
	global_load_dword v127, v[56:57], off
	v_lshl_add_u64 v[56:57], v[56:57], 0, v[8:9]
	global_load_dword v128, v[56:57], off
	v_lshl_add_u64 v[56:57], v[56:57], 0, v[8:9]
	global_load_dword v129, v[56:57], off
	v_lshl_add_u64 v[56:57], v[56:57], 0, v[8:9]
	global_load_dword v130, v[56:57], off
	v_lshl_add_u64 v[56:57], v[56:57], 0, v[8:9]
	global_load_dword v131, v[56:57], off
	v_lshl_add_u64 v[56:57], v[56:57], 0, v[8:9]
	global_load_dword v132, v[56:57], off
	v_lshl_add_u64 v[56:57], v[56:57], 0, v[8:9]
	global_load_dword v133, v[56:57], off
	v_lshl_add_u64 v[56:57], v[56:57], 0, v[8:9]
	s_waitcnt vmcnt(48)
	v_readlane_b32 s20, v12, 32
	v_readlane_b32 s21, v16, 32
	v_readlane_b32 vcc_lo, v20, 32
	v_fmac_f32_e32 v10, s20, v70
	v_fmac_f32_e32 v11, s21, v70
	v_fmac_f32_e32 v66, vcc_lo, v70
	v_readlane_b32 s20, v13, 32
	v_readlane_b32 s21, v17, 32
	v_readlane_b32 vcc_lo, v21, 32
	v_fmac_f32_e32 v10, s20, v71
	v_fmac_f32_e32 v11, s21, v71
	v_fmac_f32_e32 v66, vcc_lo, v71
	v_readlane_b32 s20, v14, 32
	v_readlane_b32 s21, v18, 32
	v_readlane_b32 vcc_lo, v22, 32
	v_fmac_f32_e32 v10, s20, v72
	v_fmac_f32_e32 v11, s21, v72
	v_fmac_f32_e32 v66, vcc_lo, v72
	v_readlane_b32 s20, v15, 32
	v_readlane_b32 s21, v19, 32
	v_readlane_b32 vcc_lo, v23, 32
	v_fmac_f32_e32 v10, s20, v73
	v_fmac_f32_e32 v11, s21, v73
	v_fmac_f32_e32 v66, vcc_lo, v73
	v_readlane_b32 s20, v12, 33
	v_readlane_b32 s21, v16, 33
	v_readlane_b32 vcc_lo, v20, 33
	v_fmac_f32_e32 v10, s20, v74
	v_fmac_f32_e32 v11, s21, v74
	v_fmac_f32_e32 v66, vcc_lo, v74
	v_readlane_b32 s20, v13, 33
	v_readlane_b32 s21, v17, 33
	v_readlane_b32 vcc_lo, v21, 33
	v_fmac_f32_e32 v10, s20, v75
	v_fmac_f32_e32 v11, s21, v75
	v_fmac_f32_e32 v66, vcc_lo, v75
	v_readlane_b32 s20, v14, 33
	v_readlane_b32 s21, v18, 33
	v_readlane_b32 vcc_lo, v22, 33
	v_fmac_f32_e32 v10, s20, v76
	v_fmac_f32_e32 v11, s21, v76
	v_fmac_f32_e32 v66, vcc_lo, v76
	v_readlane_b32 s20, v15, 33
	v_readlane_b32 s21, v19, 33
	v_readlane_b32 vcc_lo, v23, 33
	v_fmac_f32_e32 v10, s20, v77
	v_fmac_f32_e32 v11, s21, v77
	v_fmac_f32_e32 v66, vcc_lo, v77
	v_readlane_b32 s20, v12, 34
	v_readlane_b32 s21, v16, 34
	v_readlane_b32 vcc_lo, v20, 34
	v_fmac_f32_e32 v10, s20, v78
	v_fmac_f32_e32 v11, s21, v78
	v_fmac_f32_e32 v66, vcc_lo, v78
	v_readlane_b32 s20, v13, 34
	v_readlane_b32 s21, v17, 34
	v_readlane_b32 vcc_lo, v21, 34
	v_fmac_f32_e32 v10, s20, v79
	v_fmac_f32_e32 v11, s21, v79
	v_fmac_f32_e32 v66, vcc_lo, v79
	v_readlane_b32 s20, v14, 34
	v_readlane_b32 s21, v18, 34
	v_readlane_b32 vcc_lo, v22, 34
	v_fmac_f32_e32 v10, s20, v80
	v_fmac_f32_e32 v11, s21, v80
	v_fmac_f32_e32 v66, vcc_lo, v80
	v_readlane_b32 s20, v15, 34
	v_readlane_b32 s21, v19, 34
	v_readlane_b32 vcc_lo, v23, 34
	v_fmac_f32_e32 v10, s20, v81
	v_fmac_f32_e32 v11, s21, v81
	v_fmac_f32_e32 v66, vcc_lo, v81
	v_readlane_b32 s20, v12, 35
	v_readlane_b32 s21, v16, 35
	v_readlane_b32 vcc_lo, v20, 35
	v_fmac_f32_e32 v10, s20, v82
	v_fmac_f32_e32 v11, s21, v82
	v_fmac_f32_e32 v66, vcc_lo, v82
	v_readlane_b32 s20, v13, 35
	v_readlane_b32 s21, v17, 35
	v_readlane_b32 vcc_lo, v21, 35
	v_fmac_f32_e32 v10, s20, v83
	v_fmac_f32_e32 v11, s21, v83
	v_fmac_f32_e32 v66, vcc_lo, v83
	v_readlane_b32 s20, v14, 35
	v_readlane_b32 s21, v18, 35
	v_readlane_b32 vcc_lo, v22, 35
	v_fmac_f32_e32 v10, s20, v84
	v_fmac_f32_e32 v11, s21, v84
	v_fmac_f32_e32 v66, vcc_lo, v84
	v_readlane_b32 s20, v15, 35
	v_readlane_b32 s21, v19, 35
	v_readlane_b32 vcc_lo, v23, 35
	v_fmac_f32_e32 v10, s20, v85
	v_fmac_f32_e32 v11, s21, v85
	v_fmac_f32_e32 v66, vcc_lo, v85
	global_load_dword v70, v[56:57], off
	v_lshl_add_u64 v[56:57], v[56:57], 0, v[8:9]
	global_load_dword v71, v[56:57], off
	v_lshl_add_u64 v[56:57], v[56:57], 0, v[8:9]
	global_load_dword v72, v[56:57], off
	v_lshl_add_u64 v[56:57], v[56:57], 0, v[8:9]
	global_load_dword v73, v[56:57], off
	v_lshl_add_u64 v[56:57], v[56:57], 0, v[8:9]
	global_load_dword v74, v[56:57], off
	v_lshl_add_u64 v[56:57], v[56:57], 0, v[8:9]
	global_load_dword v75, v[56:57], off
	v_lshl_add_u64 v[56:57], v[56:57], 0, v[8:9]
	global_load_dword v76, v[56:57], off
	v_lshl_add_u64 v[56:57], v[56:57], 0, v[8:9]
	global_load_dword v77, v[56:57], off
	v_lshl_add_u64 v[56:57], v[56:57], 0, v[8:9]
	global_load_dword v78, v[56:57], off
	v_lshl_add_u64 v[56:57], v[56:57], 0, v[8:9]
	global_load_dword v79, v[56:57], off
	v_lshl_add_u64 v[56:57], v[56:57], 0, v[8:9]
	global_load_dword v80, v[56:57], off
	v_lshl_add_u64 v[56:57], v[56:57], 0, v[8:9]
	global_load_dword v81, v[56:57], off
	v_lshl_add_u64 v[56:57], v[56:57], 0, v[8:9]
	global_load_dword v82, v[56:57], off
	v_lshl_add_u64 v[56:57], v[56:57], 0, v[8:9]
	global_load_dword v83, v[56:57], off
	v_lshl_add_u64 v[56:57], v[56:57], 0, v[8:9]
	global_load_dword v84, v[56:57], off
	v_lshl_add_u64 v[56:57], v[56:57], 0, v[8:9]
	global_load_dword v85, v[56:57], off
	v_lshl_add_u64 v[56:57], v[56:57], 0, v[8:9]
	s_waitcnt vmcnt(48)
	v_readlane_b32 s20, v12, 36
	v_readlane_b32 s21, v16, 36
	v_readlane_b32 vcc_lo, v20, 36
	v_fmac_f32_e32 v10, s20, v86
	v_fmac_f32_e32 v11, s21, v86
	v_fmac_f32_e32 v66, vcc_lo, v86
	v_readlane_b32 s20, v13, 36
	v_readlane_b32 s21, v17, 36
	v_readlane_b32 vcc_lo, v21, 36
	v_fmac_f32_e32 v10, s20, v87
	v_fmac_f32_e32 v11, s21, v87
	v_fmac_f32_e32 v66, vcc_lo, v87
	v_readlane_b32 s20, v14, 36
	v_readlane_b32 s21, v18, 36
	v_readlane_b32 vcc_lo, v22, 36
	v_fmac_f32_e32 v10, s20, v88
	v_fmac_f32_e32 v11, s21, v88
	v_fmac_f32_e32 v66, vcc_lo, v88
	v_readlane_b32 s20, v15, 36
	v_readlane_b32 s21, v19, 36
	v_readlane_b32 vcc_lo, v23, 36
	v_fmac_f32_e32 v10, s20, v89
	v_fmac_f32_e32 v11, s21, v89
	v_fmac_f32_e32 v66, vcc_lo, v89
	v_readlane_b32 s20, v12, 37
	v_readlane_b32 s21, v16, 37
	v_readlane_b32 vcc_lo, v20, 37
	v_fmac_f32_e32 v10, s20, v90
	v_fmac_f32_e32 v11, s21, v90
	v_fmac_f32_e32 v66, vcc_lo, v90
	v_readlane_b32 s20, v13, 37
	v_readlane_b32 s21, v17, 37
	v_readlane_b32 vcc_lo, v21, 37
	v_fmac_f32_e32 v10, s20, v91
	v_fmac_f32_e32 v11, s21, v91
	v_fmac_f32_e32 v66, vcc_lo, v91
	v_readlane_b32 s20, v14, 37
	v_readlane_b32 s21, v18, 37
	v_readlane_b32 vcc_lo, v22, 37
	v_fmac_f32_e32 v10, s20, v92
	v_fmac_f32_e32 v11, s21, v92
	v_fmac_f32_e32 v66, vcc_lo, v92
	v_readlane_b32 s20, v15, 37
	v_readlane_b32 s21, v19, 37
	v_readlane_b32 vcc_lo, v23, 37
	v_fmac_f32_e32 v10, s20, v93
	v_fmac_f32_e32 v11, s21, v93
	v_fmac_f32_e32 v66, vcc_lo, v93
	v_readlane_b32 s20, v12, 38
	v_readlane_b32 s21, v16, 38
	v_readlane_b32 vcc_lo, v20, 38
	v_fmac_f32_e32 v10, s20, v94
	v_fmac_f32_e32 v11, s21, v94
	v_fmac_f32_e32 v66, vcc_lo, v94
	v_readlane_b32 s20, v13, 38
	v_readlane_b32 s21, v17, 38
	v_readlane_b32 vcc_lo, v21, 38
	v_fmac_f32_e32 v10, s20, v95
	v_fmac_f32_e32 v11, s21, v95
	v_fmac_f32_e32 v66, vcc_lo, v95
	v_readlane_b32 s20, v14, 38
	v_readlane_b32 s21, v18, 38
	v_readlane_b32 vcc_lo, v22, 38
	v_fmac_f32_e32 v10, s20, v96
	v_fmac_f32_e32 v11, s21, v96
	v_fmac_f32_e32 v66, vcc_lo, v96
	v_readlane_b32 s20, v15, 38
	v_readlane_b32 s21, v19, 38
	v_readlane_b32 vcc_lo, v23, 38
	v_fmac_f32_e32 v10, s20, v97
	v_fmac_f32_e32 v11, s21, v97
	v_fmac_f32_e32 v66, vcc_lo, v97
	v_readlane_b32 s20, v12, 39
	v_readlane_b32 s21, v16, 39
	v_readlane_b32 vcc_lo, v20, 39
	v_fmac_f32_e32 v10, s20, v98
	v_fmac_f32_e32 v11, s21, v98
	v_fmac_f32_e32 v66, vcc_lo, v98
	v_readlane_b32 s20, v13, 39
	v_readlane_b32 s21, v17, 39
	v_readlane_b32 vcc_lo, v21, 39
	v_fmac_f32_e32 v10, s20, v99
	v_fmac_f32_e32 v11, s21, v99
	v_fmac_f32_e32 v66, vcc_lo, v99
	v_readlane_b32 s20, v14, 39
	v_readlane_b32 s21, v18, 39
	v_readlane_b32 vcc_lo, v22, 39
	v_fmac_f32_e32 v10, s20, v100
	v_fmac_f32_e32 v11, s21, v100
	v_fmac_f32_e32 v66, vcc_lo, v100
	v_readlane_b32 s20, v15, 39
	v_readlane_b32 s21, v19, 39
	v_readlane_b32 vcc_lo, v23, 39
	v_fmac_f32_e32 v10, s20, v101
	v_fmac_f32_e32 v11, s21, v101
	v_fmac_f32_e32 v66, vcc_lo, v101
	global_load_dword v86, v[56:57], off
	v_lshl_add_u64 v[56:57], v[56:57], 0, v[8:9]
	global_load_dword v87, v[56:57], off
	v_lshl_add_u64 v[56:57], v[56:57], 0, v[8:9]
	global_load_dword v88, v[56:57], off
	v_lshl_add_u64 v[56:57], v[56:57], 0, v[8:9]
	global_load_dword v89, v[56:57], off
	v_lshl_add_u64 v[56:57], v[56:57], 0, v[8:9]
	global_load_dword v90, v[56:57], off
	v_lshl_add_u64 v[56:57], v[56:57], 0, v[8:9]
	global_load_dword v91, v[56:57], off
	v_lshl_add_u64 v[56:57], v[56:57], 0, v[8:9]
	global_load_dword v92, v[56:57], off
	v_lshl_add_u64 v[56:57], v[56:57], 0, v[8:9]
	global_load_dword v93, v[56:57], off
	v_lshl_add_u64 v[56:57], v[56:57], 0, v[8:9]
	global_load_dword v94, v[56:57], off
	v_lshl_add_u64 v[56:57], v[56:57], 0, v[8:9]
	global_load_dword v95, v[56:57], off
	v_lshl_add_u64 v[56:57], v[56:57], 0, v[8:9]
	global_load_dword v96, v[56:57], off
	v_lshl_add_u64 v[56:57], v[56:57], 0, v[8:9]
	global_load_dword v97, v[56:57], off
	v_lshl_add_u64 v[56:57], v[56:57], 0, v[8:9]
	global_load_dword v98, v[56:57], off
	v_lshl_add_u64 v[56:57], v[56:57], 0, v[8:9]
	global_load_dword v99, v[56:57], off
	v_lshl_add_u64 v[56:57], v[56:57], 0, v[8:9]
	global_load_dword v100, v[56:57], off
	v_lshl_add_u64 v[56:57], v[56:57], 0, v[8:9]
	global_load_dword v101, v[56:57], off
	v_lshl_add_u64 v[56:57], v[56:57], 0, v[8:9]
	s_waitcnt vmcnt(48)
	v_readlane_b32 s20, v12, 40
	v_readlane_b32 s21, v16, 40
	v_readlane_b32 vcc_lo, v20, 40
	v_fmac_f32_e32 v10, s20, v102
	v_fmac_f32_e32 v11, s21, v102
	v_fmac_f32_e32 v66, vcc_lo, v102
	v_readlane_b32 s20, v13, 40
	v_readlane_b32 s21, v17, 40
	v_readlane_b32 vcc_lo, v21, 40
	v_fmac_f32_e32 v10, s20, v103
	v_fmac_f32_e32 v11, s21, v103
	v_fmac_f32_e32 v66, vcc_lo, v103
	v_readlane_b32 s20, v14, 40
	v_readlane_b32 s21, v18, 40
	v_readlane_b32 vcc_lo, v22, 40
	v_fmac_f32_e32 v10, s20, v104
	v_fmac_f32_e32 v11, s21, v104
	v_fmac_f32_e32 v66, vcc_lo, v104
	v_readlane_b32 s20, v15, 40
	v_readlane_b32 s21, v19, 40
	v_readlane_b32 vcc_lo, v23, 40
	v_fmac_f32_e32 v10, s20, v105
	v_fmac_f32_e32 v11, s21, v105
	v_fmac_f32_e32 v66, vcc_lo, v105
	v_readlane_b32 s20, v12, 41
	v_readlane_b32 s21, v16, 41
	v_readlane_b32 vcc_lo, v20, 41
	v_fmac_f32_e32 v10, s20, v106
	v_fmac_f32_e32 v11, s21, v106
	v_fmac_f32_e32 v66, vcc_lo, v106
	v_readlane_b32 s20, v13, 41
	v_readlane_b32 s21, v17, 41
	v_readlane_b32 vcc_lo, v21, 41
	v_fmac_f32_e32 v10, s20, v107
	v_fmac_f32_e32 v11, s21, v107
	v_fmac_f32_e32 v66, vcc_lo, v107
	v_readlane_b32 s20, v14, 41
	v_readlane_b32 s21, v18, 41
	v_readlane_b32 vcc_lo, v22, 41
	v_fmac_f32_e32 v10, s20, v108
	v_fmac_f32_e32 v11, s21, v108
	v_fmac_f32_e32 v66, vcc_lo, v108
	v_readlane_b32 s20, v15, 41
	v_readlane_b32 s21, v19, 41
	v_readlane_b32 vcc_lo, v23, 41
	v_fmac_f32_e32 v10, s20, v109
	v_fmac_f32_e32 v11, s21, v109
	v_fmac_f32_e32 v66, vcc_lo, v109
	v_readlane_b32 s20, v12, 42
	v_readlane_b32 s21, v16, 42
	v_readlane_b32 vcc_lo, v20, 42
	v_fmac_f32_e32 v10, s20, v110
	v_fmac_f32_e32 v11, s21, v110
	v_fmac_f32_e32 v66, vcc_lo, v110
	v_readlane_b32 s20, v13, 42
	v_readlane_b32 s21, v17, 42
	v_readlane_b32 vcc_lo, v21, 42
	v_fmac_f32_e32 v10, s20, v111
	v_fmac_f32_e32 v11, s21, v111
	v_fmac_f32_e32 v66, vcc_lo, v111
	v_readlane_b32 s20, v14, 42
	v_readlane_b32 s21, v18, 42
	v_readlane_b32 vcc_lo, v22, 42
	v_fmac_f32_e32 v10, s20, v112
	v_fmac_f32_e32 v11, s21, v112
	v_fmac_f32_e32 v66, vcc_lo, v112
	v_readlane_b32 s20, v15, 42
	v_readlane_b32 s21, v19, 42
	v_readlane_b32 vcc_lo, v23, 42
	v_fmac_f32_e32 v10, s20, v113
	v_fmac_f32_e32 v11, s21, v113
	v_fmac_f32_e32 v66, vcc_lo, v113
	v_readlane_b32 s20, v12, 43
	v_readlane_b32 s21, v16, 43
	v_readlane_b32 vcc_lo, v20, 43
	v_fmac_f32_e32 v10, s20, v114
	v_fmac_f32_e32 v11, s21, v114
	v_fmac_f32_e32 v66, vcc_lo, v114
	v_readlane_b32 s20, v13, 43
	v_readlane_b32 s21, v17, 43
	v_readlane_b32 vcc_lo, v21, 43
	v_fmac_f32_e32 v10, s20, v115
	v_fmac_f32_e32 v11, s21, v115
	v_fmac_f32_e32 v66, vcc_lo, v115
	v_readlane_b32 s20, v14, 43
	v_readlane_b32 s21, v18, 43
	v_readlane_b32 vcc_lo, v22, 43
	v_fmac_f32_e32 v10, s20, v116
	v_fmac_f32_e32 v11, s21, v116
	v_fmac_f32_e32 v66, vcc_lo, v116
	v_readlane_b32 s20, v15, 43
	v_readlane_b32 s21, v19, 43
	v_readlane_b32 vcc_lo, v23, 43
	v_fmac_f32_e32 v10, s20, v117
	v_fmac_f32_e32 v11, s21, v117
	v_fmac_f32_e32 v66, vcc_lo, v117
	global_load_dword v102, v[56:57], off
	v_lshl_add_u64 v[56:57], v[56:57], 0, v[8:9]
	global_load_dword v103, v[56:57], off
	v_lshl_add_u64 v[56:57], v[56:57], 0, v[8:9]
	global_load_dword v104, v[56:57], off
	v_lshl_add_u64 v[56:57], v[56:57], 0, v[8:9]
	global_load_dword v105, v[56:57], off
	v_lshl_add_u64 v[56:57], v[56:57], 0, v[8:9]
	global_load_dword v106, v[56:57], off
	v_lshl_add_u64 v[56:57], v[56:57], 0, v[8:9]
	global_load_dword v107, v[56:57], off
	v_lshl_add_u64 v[56:57], v[56:57], 0, v[8:9]
	global_load_dword v108, v[56:57], off
	v_lshl_add_u64 v[56:57], v[56:57], 0, v[8:9]
	global_load_dword v109, v[56:57], off
	v_lshl_add_u64 v[56:57], v[56:57], 0, v[8:9]
	global_load_dword v110, v[56:57], off
	v_lshl_add_u64 v[56:57], v[56:57], 0, v[8:9]
	global_load_dword v111, v[56:57], off
	v_lshl_add_u64 v[56:57], v[56:57], 0, v[8:9]
	global_load_dword v112, v[56:57], off
	v_lshl_add_u64 v[56:57], v[56:57], 0, v[8:9]
	global_load_dword v113, v[56:57], off
	v_lshl_add_u64 v[56:57], v[56:57], 0, v[8:9]
	global_load_dword v114, v[56:57], off
	v_lshl_add_u64 v[56:57], v[56:57], 0, v[8:9]
	global_load_dword v115, v[56:57], off
	v_lshl_add_u64 v[56:57], v[56:57], 0, v[8:9]
	global_load_dword v116, v[56:57], off
	v_lshl_add_u64 v[56:57], v[56:57], 0, v[8:9]
	global_load_dword v117, v[56:57], off
	v_lshl_add_u64 v[56:57], v[56:57], 0, v[8:9]
	s_waitcnt vmcnt(48)
	v_readlane_b32 s20, v12, 44
	v_readlane_b32 s21, v16, 44
	v_readlane_b32 vcc_lo, v20, 44
	v_fmac_f32_e32 v10, s20, v118
	v_fmac_f32_e32 v11, s21, v118
	v_fmac_f32_e32 v66, vcc_lo, v118
	v_readlane_b32 s20, v13, 44
	v_readlane_b32 s21, v17, 44
	v_readlane_b32 vcc_lo, v21, 44
	v_fmac_f32_e32 v10, s20, v119
	v_fmac_f32_e32 v11, s21, v119
	v_fmac_f32_e32 v66, vcc_lo, v119
	v_readlane_b32 s20, v14, 44
	v_readlane_b32 s21, v18, 44
	v_readlane_b32 vcc_lo, v22, 44
	v_fmac_f32_e32 v10, s20, v120
	v_fmac_f32_e32 v11, s21, v120
	v_fmac_f32_e32 v66, vcc_lo, v120
	v_readlane_b32 s20, v15, 44
	v_readlane_b32 s21, v19, 44
	v_readlane_b32 vcc_lo, v23, 44
	v_fmac_f32_e32 v10, s20, v121
	v_fmac_f32_e32 v11, s21, v121
	v_fmac_f32_e32 v66, vcc_lo, v121
	v_readlane_b32 s20, v12, 45
	v_readlane_b32 s21, v16, 45
	v_readlane_b32 vcc_lo, v20, 45
	v_fmac_f32_e32 v10, s20, v122
	v_fmac_f32_e32 v11, s21, v122
	v_fmac_f32_e32 v66, vcc_lo, v122
	v_readlane_b32 s20, v13, 45
	v_readlane_b32 s21, v17, 45
	v_readlane_b32 vcc_lo, v21, 45
	v_fmac_f32_e32 v10, s20, v123
	v_fmac_f32_e32 v11, s21, v123
	v_fmac_f32_e32 v66, vcc_lo, v123
	v_readlane_b32 s20, v14, 45
	v_readlane_b32 s21, v18, 45
	v_readlane_b32 vcc_lo, v22, 45
	v_fmac_f32_e32 v10, s20, v124
	v_fmac_f32_e32 v11, s21, v124
	v_fmac_f32_e32 v66, vcc_lo, v124
	v_readlane_b32 s20, v15, 45
	v_readlane_b32 s21, v19, 45
	v_readlane_b32 vcc_lo, v23, 45
	v_fmac_f32_e32 v10, s20, v125
	v_fmac_f32_e32 v11, s21, v125
	v_fmac_f32_e32 v66, vcc_lo, v125
	v_readlane_b32 s20, v12, 46
	v_readlane_b32 s21, v16, 46
	v_readlane_b32 vcc_lo, v20, 46
	v_fmac_f32_e32 v10, s20, v126
	v_fmac_f32_e32 v11, s21, v126
	v_fmac_f32_e32 v66, vcc_lo, v126
	v_readlane_b32 s20, v13, 46
	v_readlane_b32 s21, v17, 46
	v_readlane_b32 vcc_lo, v21, 46
	v_fmac_f32_e32 v10, s20, v127
	v_fmac_f32_e32 v11, s21, v127
	v_fmac_f32_e32 v66, vcc_lo, v127
	v_readlane_b32 s20, v14, 46
	v_readlane_b32 s21, v18, 46
	v_readlane_b32 vcc_lo, v22, 46
	v_fmac_f32_e32 v10, s20, v128
	v_fmac_f32_e32 v11, s21, v128
	v_fmac_f32_e32 v66, vcc_lo, v128
	v_readlane_b32 s20, v15, 46
	v_readlane_b32 s21, v19, 46
	v_readlane_b32 vcc_lo, v23, 46
	v_fmac_f32_e32 v10, s20, v129
	v_fmac_f32_e32 v11, s21, v129
	v_fmac_f32_e32 v66, vcc_lo, v129
	v_readlane_b32 s20, v12, 47
	v_readlane_b32 s21, v16, 47
	v_readlane_b32 vcc_lo, v20, 47
	v_fmac_f32_e32 v10, s20, v130
	v_fmac_f32_e32 v11, s21, v130
	v_fmac_f32_e32 v66, vcc_lo, v130
	v_readlane_b32 s20, v13, 47
	v_readlane_b32 s21, v17, 47
	v_readlane_b32 vcc_lo, v21, 47
	v_fmac_f32_e32 v10, s20, v131
	v_fmac_f32_e32 v11, s21, v131
	v_fmac_f32_e32 v66, vcc_lo, v131
	v_readlane_b32 s20, v14, 47
	v_readlane_b32 s21, v18, 47
	v_readlane_b32 vcc_lo, v22, 47
	v_fmac_f32_e32 v10, s20, v132
	v_fmac_f32_e32 v11, s21, v132
	v_fmac_f32_e32 v66, vcc_lo, v132
	v_readlane_b32 s20, v15, 47
	v_readlane_b32 s21, v19, 47
	v_readlane_b32 vcc_lo, v23, 47
	v_fmac_f32_e32 v10, s20, v133
	v_fmac_f32_e32 v11, s21, v133
	v_fmac_f32_e32 v66, vcc_lo, v133
	global_load_dword v118, v[56:57], off
	v_lshl_add_u64 v[56:57], v[56:57], 0, v[8:9]
	global_load_dword v119, v[56:57], off
	v_lshl_add_u64 v[56:57], v[56:57], 0, v[8:9]
	global_load_dword v120, v[56:57], off
	v_lshl_add_u64 v[56:57], v[56:57], 0, v[8:9]
	global_load_dword v121, v[56:57], off
	v_lshl_add_u64 v[56:57], v[56:57], 0, v[8:9]
	global_load_dword v122, v[56:57], off
	v_lshl_add_u64 v[56:57], v[56:57], 0, v[8:9]
	global_load_dword v123, v[56:57], off
	v_lshl_add_u64 v[56:57], v[56:57], 0, v[8:9]
	global_load_dword v124, v[56:57], off
	v_lshl_add_u64 v[56:57], v[56:57], 0, v[8:9]
	global_load_dword v125, v[56:57], off
	v_lshl_add_u64 v[56:57], v[56:57], 0, v[8:9]
	global_load_dword v126, v[56:57], off
	v_lshl_add_u64 v[56:57], v[56:57], 0, v[8:9]
	global_load_dword v127, v[56:57], off
	v_lshl_add_u64 v[56:57], v[56:57], 0, v[8:9]
	global_load_dword v128, v[56:57], off
	v_lshl_add_u64 v[56:57], v[56:57], 0, v[8:9]
	global_load_dword v129, v[56:57], off
	v_lshl_add_u64 v[56:57], v[56:57], 0, v[8:9]
	global_load_dword v130, v[56:57], off
	v_lshl_add_u64 v[56:57], v[56:57], 0, v[8:9]
	global_load_dword v131, v[56:57], off
	v_lshl_add_u64 v[56:57], v[56:57], 0, v[8:9]
	global_load_dword v132, v[56:57], off
	v_lshl_add_u64 v[56:57], v[56:57], 0, v[8:9]
	global_load_dword v133, v[56:57], off
	v_lshl_add_u64 v[56:57], v[56:57], 0, v[8:9]
	s_waitcnt vmcnt(48)
	v_readlane_b32 s20, v12, 48
	v_readlane_b32 s21, v16, 48
	v_readlane_b32 vcc_lo, v20, 48
	v_fmac_f32_e32 v10, s20, v70
	v_fmac_f32_e32 v11, s21, v70
	v_fmac_f32_e32 v66, vcc_lo, v70
	v_readlane_b32 s20, v13, 48
	v_readlane_b32 s21, v17, 48
	v_readlane_b32 vcc_lo, v21, 48
	v_fmac_f32_e32 v10, s20, v71
	v_fmac_f32_e32 v11, s21, v71
	v_fmac_f32_e32 v66, vcc_lo, v71
	v_readlane_b32 s20, v14, 48
	v_readlane_b32 s21, v18, 48
	v_readlane_b32 vcc_lo, v22, 48
	v_fmac_f32_e32 v10, s20, v72
	v_fmac_f32_e32 v11, s21, v72
	v_fmac_f32_e32 v66, vcc_lo, v72
	v_readlane_b32 s20, v15, 48
	v_readlane_b32 s21, v19, 48
	v_readlane_b32 vcc_lo, v23, 48
	v_fmac_f32_e32 v10, s20, v73
	v_fmac_f32_e32 v11, s21, v73
	v_fmac_f32_e32 v66, vcc_lo, v73
	v_readlane_b32 s20, v12, 49
	v_readlane_b32 s21, v16, 49
	v_readlane_b32 vcc_lo, v20, 49
	v_fmac_f32_e32 v10, s20, v74
	v_fmac_f32_e32 v11, s21, v74
	v_fmac_f32_e32 v66, vcc_lo, v74
	v_readlane_b32 s20, v13, 49
	v_readlane_b32 s21, v17, 49
	v_readlane_b32 vcc_lo, v21, 49
	v_fmac_f32_e32 v10, s20, v75
	v_fmac_f32_e32 v11, s21, v75
	v_fmac_f32_e32 v66, vcc_lo, v75
	v_readlane_b32 s20, v14, 49
	v_readlane_b32 s21, v18, 49
	v_readlane_b32 vcc_lo, v22, 49
	v_fmac_f32_e32 v10, s20, v76
	v_fmac_f32_e32 v11, s21, v76
	v_fmac_f32_e32 v66, vcc_lo, v76
	v_readlane_b32 s20, v15, 49
	v_readlane_b32 s21, v19, 49
	v_readlane_b32 vcc_lo, v23, 49
	v_fmac_f32_e32 v10, s20, v77
	v_fmac_f32_e32 v11, s21, v77
	v_fmac_f32_e32 v66, vcc_lo, v77
	v_readlane_b32 s20, v12, 50
	v_readlane_b32 s21, v16, 50
	v_readlane_b32 vcc_lo, v20, 50
	v_fmac_f32_e32 v10, s20, v78
	v_fmac_f32_e32 v11, s21, v78
	v_fmac_f32_e32 v66, vcc_lo, v78
	v_readlane_b32 s20, v13, 50
	v_readlane_b32 s21, v17, 50
	v_readlane_b32 vcc_lo, v21, 50
	v_fmac_f32_e32 v10, s20, v79
	v_fmac_f32_e32 v11, s21, v79
	v_fmac_f32_e32 v66, vcc_lo, v79
	v_readlane_b32 s20, v14, 50
	v_readlane_b32 s21, v18, 50
	v_readlane_b32 vcc_lo, v22, 50
	v_fmac_f32_e32 v10, s20, v80
	v_fmac_f32_e32 v11, s21, v80
	v_fmac_f32_e32 v66, vcc_lo, v80
	v_readlane_b32 s20, v15, 50
	v_readlane_b32 s21, v19, 50
	v_readlane_b32 vcc_lo, v23, 50
	v_fmac_f32_e32 v10, s20, v81
	v_fmac_f32_e32 v11, s21, v81
	v_fmac_f32_e32 v66, vcc_lo, v81
	v_readlane_b32 s20, v12, 51
	v_readlane_b32 s21, v16, 51
	v_readlane_b32 vcc_lo, v20, 51
	v_fmac_f32_e32 v10, s20, v82
	v_fmac_f32_e32 v11, s21, v82
	v_fmac_f32_e32 v66, vcc_lo, v82
	v_readlane_b32 s20, v13, 51
	v_readlane_b32 s21, v17, 51
	v_readlane_b32 vcc_lo, v21, 51
	v_fmac_f32_e32 v10, s20, v83
	v_fmac_f32_e32 v11, s21, v83
	v_fmac_f32_e32 v66, vcc_lo, v83
	v_readlane_b32 s20, v14, 51
	v_readlane_b32 s21, v18, 51
	v_readlane_b32 vcc_lo, v22, 51
	v_fmac_f32_e32 v10, s20, v84
	v_fmac_f32_e32 v11, s21, v84
	v_fmac_f32_e32 v66, vcc_lo, v84
	v_readlane_b32 s20, v15, 51
	v_readlane_b32 s21, v19, 51
	v_readlane_b32 vcc_lo, v23, 51
	v_fmac_f32_e32 v10, s20, v85
	v_fmac_f32_e32 v11, s21, v85
	v_fmac_f32_e32 v66, vcc_lo, v85
	s_waitcnt vmcnt(32)
	v_readlane_b32 s20, v12, 52
	v_readlane_b32 s21, v16, 52
	v_readlane_b32 vcc_lo, v20, 52
	v_fmac_f32_e32 v10, s20, v86
	v_fmac_f32_e32 v11, s21, v86
	v_fmac_f32_e32 v66, vcc_lo, v86
	v_readlane_b32 s20, v13, 52
	v_readlane_b32 s21, v17, 52
	v_readlane_b32 vcc_lo, v21, 52
	v_fmac_f32_e32 v10, s20, v87
	v_fmac_f32_e32 v11, s21, v87
	v_fmac_f32_e32 v66, vcc_lo, v87
	v_readlane_b32 s20, v14, 52
	v_readlane_b32 s21, v18, 52
	v_readlane_b32 vcc_lo, v22, 52
	v_fmac_f32_e32 v10, s20, v88
	v_fmac_f32_e32 v11, s21, v88
	v_fmac_f32_e32 v66, vcc_lo, v88
	v_readlane_b32 s20, v15, 52
	v_readlane_b32 s21, v19, 52
	v_readlane_b32 vcc_lo, v23, 52
	v_fmac_f32_e32 v10, s20, v89
	v_fmac_f32_e32 v11, s21, v89
	v_fmac_f32_e32 v66, vcc_lo, v89
	v_readlane_b32 s20, v12, 53
	v_readlane_b32 s21, v16, 53
	v_readlane_b32 vcc_lo, v20, 53
	v_fmac_f32_e32 v10, s20, v90
	v_fmac_f32_e32 v11, s21, v90
	v_fmac_f32_e32 v66, vcc_lo, v90
	v_readlane_b32 s20, v13, 53
	v_readlane_b32 s21, v17, 53
	v_readlane_b32 vcc_lo, v21, 53
	v_fmac_f32_e32 v10, s20, v91
	v_fmac_f32_e32 v11, s21, v91
	v_fmac_f32_e32 v66, vcc_lo, v91
	v_readlane_b32 s20, v14, 53
	v_readlane_b32 s21, v18, 53
	v_readlane_b32 vcc_lo, v22, 53
	v_fmac_f32_e32 v10, s20, v92
	v_fmac_f32_e32 v11, s21, v92
	v_fmac_f32_e32 v66, vcc_lo, v92
	v_readlane_b32 s20, v15, 53
	v_readlane_b32 s21, v19, 53
	v_readlane_b32 vcc_lo, v23, 53
	v_fmac_f32_e32 v10, s20, v93
	v_fmac_f32_e32 v11, s21, v93
	v_fmac_f32_e32 v66, vcc_lo, v93
	v_readlane_b32 s20, v12, 54
	v_readlane_b32 s21, v16, 54
	v_readlane_b32 vcc_lo, v20, 54
	v_fmac_f32_e32 v10, s20, v94
	v_fmac_f32_e32 v11, s21, v94
	v_fmac_f32_e32 v66, vcc_lo, v94
	v_readlane_b32 s20, v13, 54
	v_readlane_b32 s21, v17, 54
	v_readlane_b32 vcc_lo, v21, 54
	v_fmac_f32_e32 v10, s20, v95
	v_fmac_f32_e32 v11, s21, v95
	v_fmac_f32_e32 v66, vcc_lo, v95
	v_readlane_b32 s20, v14, 54
	v_readlane_b32 s21, v18, 54
	v_readlane_b32 vcc_lo, v22, 54
	v_fmac_f32_e32 v10, s20, v96
	v_fmac_f32_e32 v11, s21, v96
	v_fmac_f32_e32 v66, vcc_lo, v96
	v_readlane_b32 s20, v15, 54
	v_readlane_b32 s21, v19, 54
	v_readlane_b32 vcc_lo, v23, 54
	v_fmac_f32_e32 v10, s20, v97
	v_fmac_f32_e32 v11, s21, v97
	v_fmac_f32_e32 v66, vcc_lo, v97
	v_readlane_b32 s20, v12, 55
	v_readlane_b32 s21, v16, 55
	v_readlane_b32 vcc_lo, v20, 55
	v_fmac_f32_e32 v10, s20, v98
	v_fmac_f32_e32 v11, s21, v98
	v_fmac_f32_e32 v66, vcc_lo, v98
	v_readlane_b32 s20, v13, 55
	v_readlane_b32 s21, v17, 55
	v_readlane_b32 vcc_lo, v21, 55
	v_fmac_f32_e32 v10, s20, v99
	v_fmac_f32_e32 v11, s21, v99
	v_fmac_f32_e32 v66, vcc_lo, v99
	v_readlane_b32 s20, v14, 55
	v_readlane_b32 s21, v18, 55
	v_readlane_b32 vcc_lo, v22, 55
	v_fmac_f32_e32 v10, s20, v100
	v_fmac_f32_e32 v11, s21, v100
	v_fmac_f32_e32 v66, vcc_lo, v100
	v_readlane_b32 s20, v15, 55
	v_readlane_b32 s21, v19, 55
	v_readlane_b32 vcc_lo, v23, 55
	v_fmac_f32_e32 v10, s20, v101
	v_fmac_f32_e32 v11, s21, v101
	v_fmac_f32_e32 v66, vcc_lo, v101
	s_waitcnt vmcnt(16)
	v_readlane_b32 s20, v12, 56
	v_readlane_b32 s21, v16, 56
	v_readlane_b32 vcc_lo, v20, 56
	v_fmac_f32_e32 v10, s20, v102
	v_fmac_f32_e32 v11, s21, v102
	v_fmac_f32_e32 v66, vcc_lo, v102
	v_readlane_b32 s20, v13, 56
	v_readlane_b32 s21, v17, 56
	v_readlane_b32 vcc_lo, v21, 56
	v_fmac_f32_e32 v10, s20, v103
	v_fmac_f32_e32 v11, s21, v103
	v_fmac_f32_e32 v66, vcc_lo, v103
	v_readlane_b32 s20, v14, 56
	v_readlane_b32 s21, v18, 56
	v_readlane_b32 vcc_lo, v22, 56
	v_fmac_f32_e32 v10, s20, v104
	v_fmac_f32_e32 v11, s21, v104
	v_fmac_f32_e32 v66, vcc_lo, v104
	v_readlane_b32 s20, v15, 56
	v_readlane_b32 s21, v19, 56
	v_readlane_b32 vcc_lo, v23, 56
	v_fmac_f32_e32 v10, s20, v105
	v_fmac_f32_e32 v11, s21, v105
	v_fmac_f32_e32 v66, vcc_lo, v105
	v_readlane_b32 s20, v12, 57
	v_readlane_b32 s21, v16, 57
	v_readlane_b32 vcc_lo, v20, 57
	v_fmac_f32_e32 v10, s20, v106
	v_fmac_f32_e32 v11, s21, v106
	v_fmac_f32_e32 v66, vcc_lo, v106
	v_readlane_b32 s20, v13, 57
	v_readlane_b32 s21, v17, 57
	v_readlane_b32 vcc_lo, v21, 57
	v_fmac_f32_e32 v10, s20, v107
	v_fmac_f32_e32 v11, s21, v107
	v_fmac_f32_e32 v66, vcc_lo, v107
	v_readlane_b32 s20, v14, 57
	v_readlane_b32 s21, v18, 57
	v_readlane_b32 vcc_lo, v22, 57
	v_fmac_f32_e32 v10, s20, v108
	v_fmac_f32_e32 v11, s21, v108
	v_fmac_f32_e32 v66, vcc_lo, v108
	v_readlane_b32 s20, v15, 57
	v_readlane_b32 s21, v19, 57
	v_readlane_b32 vcc_lo, v23, 57
	v_fmac_f32_e32 v10, s20, v109
	v_fmac_f32_e32 v11, s21, v109
	v_fmac_f32_e32 v66, vcc_lo, v109
	v_readlane_b32 s20, v12, 58
	v_readlane_b32 s21, v16, 58
	v_readlane_b32 vcc_lo, v20, 58
	v_fmac_f32_e32 v10, s20, v110
	v_fmac_f32_e32 v11, s21, v110
	v_fmac_f32_e32 v66, vcc_lo, v110
	v_readlane_b32 s20, v13, 58
	v_readlane_b32 s21, v17, 58
	v_readlane_b32 vcc_lo, v21, 58
	v_fmac_f32_e32 v10, s20, v111
	v_fmac_f32_e32 v11, s21, v111
	v_fmac_f32_e32 v66, vcc_lo, v111
	v_readlane_b32 s20, v14, 58
	v_readlane_b32 s21, v18, 58
	v_readlane_b32 vcc_lo, v22, 58
	v_fmac_f32_e32 v10, s20, v112
	v_fmac_f32_e32 v11, s21, v112
	v_fmac_f32_e32 v66, vcc_lo, v112
	v_readlane_b32 s20, v15, 58
	v_readlane_b32 s21, v19, 58
	v_readlane_b32 vcc_lo, v23, 58
	v_fmac_f32_e32 v10, s20, v113
	v_fmac_f32_e32 v11, s21, v113
	v_fmac_f32_e32 v66, vcc_lo, v113
	v_readlane_b32 s20, v12, 59
	v_readlane_b32 s21, v16, 59
	v_readlane_b32 vcc_lo, v20, 59
	v_fmac_f32_e32 v10, s20, v114
	v_fmac_f32_e32 v11, s21, v114
	v_fmac_f32_e32 v66, vcc_lo, v114
	v_readlane_b32 s20, v13, 59
	v_readlane_b32 s21, v17, 59
	v_readlane_b32 vcc_lo, v21, 59
	v_fmac_f32_e32 v10, s20, v115
	v_fmac_f32_e32 v11, s21, v115
	v_fmac_f32_e32 v66, vcc_lo, v115
	v_readlane_b32 s20, v14, 59
	v_readlane_b32 s21, v18, 59
	v_readlane_b32 vcc_lo, v22, 59
	v_fmac_f32_e32 v10, s20, v116
	v_fmac_f32_e32 v11, s21, v116
	v_fmac_f32_e32 v66, vcc_lo, v116
	v_readlane_b32 s20, v15, 59
	v_readlane_b32 s21, v19, 59
	v_readlane_b32 vcc_lo, v23, 59
	v_fmac_f32_e32 v10, s20, v117
	v_fmac_f32_e32 v11, s21, v117
	v_fmac_f32_e32 v66, vcc_lo, v117
	s_waitcnt vmcnt(0)
	v_readlane_b32 s20, v12, 60
	v_readlane_b32 s21, v16, 60
	v_readlane_b32 vcc_lo, v20, 60
	v_fmac_f32_e32 v10, s20, v118
	v_fmac_f32_e32 v11, s21, v118
	v_fmac_f32_e32 v66, vcc_lo, v118
	v_readlane_b32 s20, v13, 60
	v_readlane_b32 s21, v17, 60
	v_readlane_b32 vcc_lo, v21, 60
	v_fmac_f32_e32 v10, s20, v119
	v_fmac_f32_e32 v11, s21, v119
	v_fmac_f32_e32 v66, vcc_lo, v119
	v_readlane_b32 s20, v14, 60
	v_readlane_b32 s21, v18, 60
	v_readlane_b32 vcc_lo, v22, 60
	v_fmac_f32_e32 v10, s20, v120
	v_fmac_f32_e32 v11, s21, v120
	v_fmac_f32_e32 v66, vcc_lo, v120
	v_readlane_b32 s20, v15, 60
	v_readlane_b32 s21, v19, 60
	v_readlane_b32 vcc_lo, v23, 60
	v_fmac_f32_e32 v10, s20, v121
	v_fmac_f32_e32 v11, s21, v121
	v_fmac_f32_e32 v66, vcc_lo, v121
	v_readlane_b32 s20, v12, 61
	v_readlane_b32 s21, v16, 61
	v_readlane_b32 vcc_lo, v20, 61
	v_fmac_f32_e32 v10, s20, v122
	v_fmac_f32_e32 v11, s21, v122
	v_fmac_f32_e32 v66, vcc_lo, v122
	v_readlane_b32 s20, v13, 61
	v_readlane_b32 s21, v17, 61
	v_readlane_b32 vcc_lo, v21, 61
	v_fmac_f32_e32 v10, s20, v123
	v_fmac_f32_e32 v11, s21, v123
	v_fmac_f32_e32 v66, vcc_lo, v123
	v_readlane_b32 s20, v14, 61
	v_readlane_b32 s21, v18, 61
	v_readlane_b32 vcc_lo, v22, 61
	v_fmac_f32_e32 v10, s20, v124
	v_fmac_f32_e32 v11, s21, v124
	v_fmac_f32_e32 v66, vcc_lo, v124
	v_readlane_b32 s20, v15, 61
	v_readlane_b32 s21, v19, 61
	v_readlane_b32 vcc_lo, v23, 61
	v_fmac_f32_e32 v10, s20, v125
	v_fmac_f32_e32 v11, s21, v125
	v_fmac_f32_e32 v66, vcc_lo, v125
	v_readlane_b32 s20, v12, 62
	v_readlane_b32 s21, v16, 62
	v_readlane_b32 vcc_lo, v20, 62
	v_fmac_f32_e32 v10, s20, v126
	v_fmac_f32_e32 v11, s21, v126
	v_fmac_f32_e32 v66, vcc_lo, v126
	v_readlane_b32 s20, v13, 62
	v_readlane_b32 s21, v17, 62
	v_readlane_b32 vcc_lo, v21, 62
	v_fmac_f32_e32 v10, s20, v127
	v_fmac_f32_e32 v11, s21, v127
	v_fmac_f32_e32 v66, vcc_lo, v127
	v_readlane_b32 s20, v14, 62
	v_readlane_b32 s21, v18, 62
	v_readlane_b32 vcc_lo, v22, 62
	v_fmac_f32_e32 v10, s20, v128
	v_fmac_f32_e32 v11, s21, v128
	v_fmac_f32_e32 v66, vcc_lo, v128
	v_readlane_b32 s20, v15, 62
	v_readlane_b32 s21, v19, 62
	v_readlane_b32 vcc_lo, v23, 62
	v_fmac_f32_e32 v10, s20, v129
	v_fmac_f32_e32 v11, s21, v129
	v_fmac_f32_e32 v66, vcc_lo, v129
	v_readlane_b32 s20, v12, 63
	v_readlane_b32 s21, v16, 63
	v_readlane_b32 vcc_lo, v20, 63
	v_fmac_f32_e32 v10, s20, v130
	v_fmac_f32_e32 v11, s21, v130
	v_fmac_f32_e32 v66, vcc_lo, v130
	v_readlane_b32 s20, v13, 63
	v_readlane_b32 s21, v17, 63
	v_readlane_b32 vcc_lo, v21, 63
	v_fmac_f32_e32 v10, s20, v131
	v_fmac_f32_e32 v11, s21, v131
	v_fmac_f32_e32 v66, vcc_lo, v131
	v_readlane_b32 s20, v14, 63
	v_readlane_b32 s21, v18, 63
	v_readlane_b32 vcc_lo, v22, 63
	v_fmac_f32_e32 v10, s20, v132
	v_fmac_f32_e32 v11, s21, v132
	v_fmac_f32_e32 v66, vcc_lo, v132
	v_readlane_b32 s20, v15, 63
	v_readlane_b32 s21, v19, 63
	v_readlane_b32 vcc_lo, v23, 63
	v_fmac_f32_e32 v10, s20, v133
	v_fmac_f32_e32 v11, s21, v133
	v_fmac_f32_e32 v66, vcc_lo, v133
	v_mul_lo_u32 v2, v0, s74
	s_movk_i32 s4, 0xc0
	v_lshl_or_b32 v2, v51, 2, v2
	v_cmp_gt_i32_e32 vcc, s4, v50
	s_barrier
	ds_write2st64_b32 v2, v10, v11 offset1:1
	ds_write_b32 v2, v66 offset:512
	s_waitcnt lgkmcnt(0)
	s_barrier
	s_and_saveexec_b64 s[4:5], vcc
	s_cbranch_execz .LBB0_28
	v_lshlrev_b32_e32 v2, 2, v50
	s_mov_b32 s20, 0x3fffffc0
	ds_read_b32 v4, v2
	v_and_or_b32 v2, v50, s20, v51
	v_lshlrev_b32_e32 v5, 2, v2
	ds_read2st64_b32 v[2:3], v5 offset0:3 offset1:6
	s_mul_i32 s20, s22, 0x1800
	v_readlane_b32 s52, v254, 42
	v_readlane_b32 s64, v254, 54
	v_readlane_b32 s65, v254, 55
	s_waitcnt lgkmcnt(0)
	v_add_f32_e32 v2, v4, v2
	v_add_f32_e32 v2, v2, v3
	ds_read_b32 v3, v5 offset:2304
	v_readlane_b32 s53, v254, 43
	v_readlane_b32 s54, v254, 44
	v_readlane_b32 s55, v254, 45
	v_readlane_b32 s56, v254, 46
	s_waitcnt lgkmcnt(0)
	v_add_f32_e32 v4, v2, v3
	v_add_u32_e32 v2, s20, v52
	v_ashrrev_i32_e32 v3, 31, v2
	v_lshl_add_u64 v[2:3], v[2:3], 2, s[64:65]
	global_load_dword v2, v[2:3], off
	v_readlane_b32 s57, v254, 47
	v_readlane_b32 s58, v254, 48
	v_readlane_b32 s59, v254, 49
	v_readlane_b32 s60, v254, 50
	v_readlane_b32 s61, v254, 51
	v_readlane_b32 s62, v254, 52
	v_readlane_b32 s63, v254, 53
	v_readlane_b32 s66, v254, 56
	v_readlane_b32 s67, v254, 57
	s_waitcnt vmcnt(0)
	v_add_f32_e32 v6, v4, v2
	v_mad_u64_u32 v[2:3], s[20:21], s22, 3, v[0:1]
	v_mov_b64_e32 v[4:5], s[72:73]
	v_mad_i64_i32 v[2:3], s[20:21], v2, s37, v[4:5]
	v_lshl_add_u64 v[2:3], v[52:53], 2, v[2:3]
	global_store_dword v[2:3], v6, off
	s_branch .LBB0_28
